# attention Y stage trimmed: no per-step negm copy (even X reads the canonical tuple, tail rebuilds it), no always-false alpha compare, no canonicalising self-max
# speedup vs baseline: 1.0243x; 1.0052x over previous
; #define LAS __attribute__((address_space(3)))
; __device__ __forceinline__ int fresh_lane() { int l; asm volatile("v_mbcnt_lo_u32_b32 %0, -1, 0\n\tv_mbcnt_hi_u32_b32 %0, -1, %0" : "=v"(l)); return l; }
; __device__ __forceinline__ int v_st(int k, int c) { const int kk = (k & ~0xC) | ((k & 4) << 1) | ((k & 8) >> 1); return ((kk >> 3) * 4 + (c >> 5)) * 512 + ((kk & 7) * 32 + (c & 31)) * 2; }
; __device__ __forceinline__ void attn_pass(const bf16_t* __restrict__ Qb, const bf16_t* __restrict__ Kh, const bf16_t* __restrict__ Vh, int seq, LAS char* lds, const int wid, f32x16 (&o)[4], float (&rli)[16]) {
;     const int lane = fresh_lane(), tid = wid * 64 + lane, r32 = lane & 31, hi = lane >> 5;
;     LAS char* V_lds = lds; LAS char* K_lds = lds + OFF_K;
;     LAS float* ws = (LAS float*)(lds + OFF_WS) + wid * 64; LAS float* li_l = ws; LAS float* al_l = ws + 32;
;     float mhat = 0.f, l_reg = 0; f32x16 negm = f32x16{};
; #pragma unroll
;     for (int d = 0; d < 4; ++d) o[d] = f32x16{};
;     bf16x8 qr[4];
;     const bf16_t* Qw = Qb + (size_t)(wid * QBLK + r32) * LDX + hi * 8;
; #pragma unroll
;     for (int d0 = 0; d0 < 4; ++d0) qr[d0] = *(const bf16x8*)(Qw + d0 * 16);
;     const int sr = tid >> 4, sc = (tid & 15) * 8, vst0 = v_st(sr, sc), vst1 = v_st(32 + sr, sc);
;     const int kr = tid >> 3, kc = (tid & 7) * 8, kst = KSWZ(kr, kc * 2);
;     const int vb0 = (int)(unsigned)(uintptr_t)V_lds + v_rd_base(lane);
;     struct { bf16x8 vs0, vs1, ks0; } sr_[2];
;     ...
;     f32x16 pA0, pA1; float alA; bf16x8 pa0, pa1, pa2, pa3; const int NT = seq / KVBLK;
;     ...
;     const bool lag = wid >= 4;
;     SLOAD(0, 0); asm volatile("s_waitcnt vmcnt(0)" ::: "memory"); SWRITE(0, 0);
;     SLOAD(1, KVBLK); SLOAD(0, 2 * KVBLK);
;     __syncthreads();
; __global__ void __launch_bounds__(NTHREADS, 2) mega(Args a) {
;     ...
;                 for (int unit = vcu; unit < 512; unit += G) {
;                     const int bh = unit / NQB, qb = unit % NQB, b = bh >> 2, h = bh & 3;
;                     const size_t row0 = (size_t)b * L + (size_t)qb * 256;
;                     f32x16 o[4]; float rli[16];
;                     att::attn_pass(Qb + row0 * 512 + h * 128, Kb + (size_t)b * L * 512 + h * 128, Vb + (size_t)b * L * 512 + h * 128, L, (LAS char*)lds, wave, o, rli);
.LBB0_586:
	s_abs_i32 s3, s53
	s_mul_hi_u32 s4, s3, s52
	s_mul_i32 s5, s4, s44
	s_sub_i32 s3, s3, s5
	s_ashr_i32 s2, s53, 31
	s_add_i32 s5, s4, 1
	s_sub_i32 s18, s3, s44
	s_cmp_ge_u32 s3, s44
	s_cselect_b32 s4, s5, s4
	s_cselect_b32 s3, s18, s3
	s_add_i32 s5, s4, 1
	s_cmp_ge_u32 s3, s44
	s_cselect_b32 s3, s5, s4
	s_xor_b32 s3, s3, s2
	s_sub_i32 s18, s3, s2
	s_mul_i32 s2, s18, s44
	s_ashr_i32 s4, s18, 2
	s_sub_i32 s2, s53, s2
	s_ashr_i32 s5, s4, 31
	v_readlane_b32 s3, v255, 45
	s_lshl_b64 s[34:35], s[4:5], s3
	s_ashr_i32 s3, s2, 31
	s_lshl_b64 s[2:3], s[2:3], 8
	s_add_u32 s42, s34, s2
	s_addc_u32 s43, s35, s3
	s_mov_b64 s[2:3], s[96:97]
	s_lshl_b64 s[4:5], s[42:43], 10
	s_add_u32 s2, s2, s4
	s_addc_u32 s3, s3, s5
	s_lshl_b32 s36, s18, 7
	s_and_b32 s4, s36, 0x180
	s_lshl_b32 s84, s4, 1
	s_add_u32 s38, s2, s84
	s_addc_u32 s39, s3, 0
	s_mov_b64 s[2:3], s[96:97]
	s_lshl_b64 s[18:19], s[34:35], 10
	s_add_u32 s4, s2, s18
	s_addc_u32 s5, s3, s19
	s_add_u32 s40, s4, s84
	s_addc_u32 s41, s5, 0
	s_mov_b64 s[4:5], s[96:97]
	s_add_u32 s46, s4, s18
	s_addc_u32 s47, s5, s19
	s_add_u32 s46, s46, s84
	v_mbcnt_lo_u32_b32 v56, -1, 0
	v_mbcnt_hi_u32_b32 v56, -1, v56
	s_addc_u32 s47, s47, 0
	v_add_u32_e32 v26, s25, v56
	v_and_b32_e32 v57, 31, v56
	v_ashrrev_i32_e32 v16, 4, v26
	s_add_u32 s46, s46, 0xef00000
	v_or_b32_e32 v0, s95, v57
	v_lshlrev_b32_e32 v58, 3, v56
	v_ashrrev_i32_e32 v17, 31, v16
	s_addc_u32 s47, s47, 0
	v_lshlrev_b64 v[14:15], 10, v[0:1]
	v_and_b32_e32 v0, 0x78, v58
	v_add_u32_e32 v18, 32, v16
	v_ashrrev_i32_e32 v20, 3, v26
	v_lshlrev_b64 v[46:47], 10, v[16:17]
	v_lshl_add_u64 v[2:3], s[46:47], 0, v[46:47]
	v_lshlrev_b32_e32 v0, 1, v0
	v_ashrrev_i32_e32 v19, 31, v18
	v_ashrrev_i32_e32 v21, 31, v20
	v_lshlrev_b32_e32 v59, 4, v56
	v_lshl_add_u64 v[50:51], v[2:3], 0, v[0:1]
	v_lshlrev_b64 v[2:3], 10, v[18:19]
	v_lshlrev_b64 v[48:49], 10, v[20:21]
	v_and_b32_e32 v22, 0x70, v59
	v_lshl_add_u64 v[2:3], s[46:47], 0, v[2:3]
	v_lshl_add_u64 v[10:11], s[40:41], 0, v[48:49]
	v_mov_b32_e32 v23, v1
	v_lshl_add_u64 v[6:7], v[2:3], 0, v[0:1]
	v_lshl_add_u64 v[52:53], v[10:11], 0, v[22:23]
	s_mov_b32 s40, 0xcf00000
	global_load_dwordx4 v[2:5], v[50:51], off
	s_nop 0
	global_load_dwordx4 v[6:9], v[6:7], off
	v_add_co_u32_e32 v10, vcc, s40, v52
	v_ashrrev_i32_e32 v0, 5, v56
	s_nop 0
	v_addc_co_u32_e32 v11, vcc, 0, v53, vcc
	global_load_dwordx4 v[10:13], v[10:11], off
	v_lshlrev_b32_e32 v24, 3, v0
	v_lshl_add_u64 v[14:15], s[38:39], 0, v[14:15]
	v_ashrrev_i32_e32 v25, 31, v24
	v_lshl_add_u64 v[14:15], v[24:25], 1, v[14:15]
	v_lshl_add_u64 v[24:25], v[14:15], 0, s[60:61]
	v_add_co_u32_e32 v14, vcc, s48, v14
	v_bfe_u32 v17, v58, 5, 2
	s_nop 0
	v_addc_co_u32_e32 v15, vcc, 0, v15, vcc
	global_load_dwordx4 v[152:155], v[24:25], off offset:32
	global_load_dwordx4 v[148:151], v[24:25], off offset:64
	global_load_dwordx4 v[156:159], v[14:15], off
	global_load_dwordx4 v[144:147], v[24:25], off offset:96
	v_and_b32_e32 v14, 0xfffff0, v16
	v_lshlrev_b32_e32 v15, 1, v16
	v_and_or_b32 v14, v15, 8, v14
	v_lshrrev_b32_e32 v15, 1, v16
	v_lshrrev_b32_e32 v14, 1, v14
	v_and_b32_e32 v16, 3, v16
	v_or_b32_e32 v14, v14, v17
	v_and_or_b32 v15, v15, 4, v16
	v_lshlrev_b32_e32 v14, 9, v14
	v_lshlrev_b32_e32 v15, 6, v15
	v_and_b32_e32 v16, 48, v59
	v_or3_b32 v233, v14, v15, v16
	v_and_b32_e32 v14, 0xfffff0, v18
	v_lshlrev_b32_e32 v18, 1, v18
	v_and_or_b32 v14, v18, 8, v14
	v_lshrrev_b32_e32 v14, 1, v14
	v_or_b32_e32 v14, v14, v17
	v_lshlrev_b32_e32 v14, 9, v14
	v_add_u32_e32 v64, 0, v233
	s_mov_b32 s38, 0x10000
	v_or3_b32 v234, v14, v15, v16
	v_lshlrev_b32_e32 v14, 7, v20
	v_and_b32_e32 v15, 0x70, v26
	s_waitcnt vmcnt(0)
	v_bitop3_b32 v54, v22, v14, v15 bitop3:0xde
	s_add_i32 s60, 0, 0x10000
	v_add_u32_e32 v65, 0, v234
	v_add_u32_e32 v235, s60, v54
	v_lshlrev_b32_e32 v230, 4, v0
	v_lshlrev_b32_e32 v236, 7, v57
	v_add_u32_e32 v241, s60, v236
	s_waitcnt vmcnt(6)
	ds_write_b128 v64, v[2:5]
	v_add_co_u32_e32 v2, vcc, s38, v50
	s_mov_b32 s38, 0x18000
	s_nop 0
	v_addc_co_u32_e32 v3, vcc, 0, v51, vcc
	v_add_co_u32_e32 v4, vcc, s38, v50
	s_waitcnt vmcnt(5)
	ds_write_b128 v65, v[6:9]
	s_waitcnt vmcnt(4)
	ds_write_b128 v235, v[10:13]
	v_addc_co_u32_e32 v5, vcc, 0, v51, vcc
	s_mov_b32 s38, 0xcf10000
	global_load_dwordx4 v[34:37], v[2:3], off
	global_load_dwordx4 v[38:41], v[4:5], off
	v_add_co_u32_e32 v2, vcc, s38, v52
	s_mov_b32 s38, 0x20000
	s_nop 0
	v_addc_co_u32_e32 v3, vcc, 0, v53, vcc
	global_load_dwordx4 v[42:45], v[2:3], off
	v_add_co_u32_e32 v2, vcc, s38, v50
	s_mov_b32 s38, 0x28000
	s_nop 0
	v_addc_co_u32_e32 v3, vcc, 0, v51, vcc
	v_add_co_u32_e32 v4, vcc, s38, v50
	s_mov_b32 s38, 0xcf20000
	s_nop 0
	v_addc_co_u32_e32 v5, vcc, 0, v51, vcc
	global_load_dwordx4 v[160:163], v[2:3], off
	global_load_dwordx4 v[164:167], v[4:5], off
	v_add_co_u32_e32 v2, vcc, s38, v52
	s_movk_i32 s38, 0x70
	v_bitop3_b32 v237, v58, v230, s38 bitop3:0x6c
	v_addc_co_u32_e32 v3, vcc, 0, v53, vcc
	v_add_u32_e32 v0, v241, v237
	global_load_dwordx4 v[168:171], v[2:3], off
	s_waitcnt lgkmcnt(0)
	s_barrier
; #define SWRITE(b, i) do { *(LAS bf16x8*)(V_lds + (b) * SHM_V + vst0) = sr_[i].vs0; *(LAS bf16x8*)(V_lds + (b) * SHM_V + vst1) = sr_[i].vs1; \
;     *(LAS bf16x8*)(K_lds + (b) * SHM_K + kst) = sr_[i].ks0; } while (0)
; __device__ __forceinline__ void partialSM(f32x16& p0, f32x16& p1, float& mhat, f32x16& negm, float& alpha, const bool first) {
;     constexpr float THRL = THR * 1.4426950408889634f;
;     float pmax = p0[0];
; #pragma unroll
;     for (int r = 1; r < 16; ++r) pmax = fmaxf(pmax, p0[r]);
; #pragma unroll
;     for (int r = 0; r < 16; ++r) pmax = fmaxf(pmax, p1[r]);
;     { auto rr = __builtin_amdgcn_permlane32_swap(__float_as_uint(pmax), __float_as_uint(pmax), false, false);
;       pmax = fmaxf(__uint_as_float(rr[0]), __uint_as_float(rr[1])); }
;     if (__builtin_expect(!first && __all(pmax <= THRL), 1)) { alpha = 1.f; }
;     else { const float dl = first ? pmax : fmaxf(pmax, 0.f); mhat += dl; alpha = first ? 0.f : __builtin_amdgcn_exp2f(-dl);
; #pragma unroll
;         for (int r = 0; r < 16; ++r) { p0[r] -= dl; p1[r] -= dl; }
; #pragma unroll
;         for (int r = 0; r < 16; ++r) negm[r] = -mhat; }
; #pragma unroll
;     for (int r = 0; r < 16; ++r) p0[r] = __builtin_amdgcn_exp2f(p0[r]);
; }
; __device__ __forceinline__ void finishSM(f32x16& p0, f32x16& p1, float alpha, float& l_reg, bf16x8& pa0, bf16x8& pa1, bf16x8& pa2, bf16x8& pa3) {
; #pragma unroll
;     for (int r = 0; r < 16; ++r) p1[r] = __builtin_amdgcn_exp2f(p1[r]);
;     float ps = 0;
; #pragma unroll
;     for (int r = 0; r < 16; ++r) ps += p0[r];
; #pragma unroll
;     for (int r = 0; r < 16; ++r) ps += p1[r];
;     { auto rr = __builtin_amdgcn_permlane32_swap(__float_as_uint(ps), __float_as_uint(ps), false, false);
;       ps = __uint_as_float(rr[0]) + __uint_as_float(rr[1]); }
;     l_reg = l_reg * alpha + ps;
;     ...
;     PK4(p0, 0, pa0); PK4(p0, 8, pa1); PK4(p1, 0, pa2); PK4(p1, 8, pa3);
;     ...
; }
; __device__ __forceinline__ void attn_pass(const bf16_t* __restrict__ Qb, const bf16_t* __restrict__ Kh, const bf16_t* __restrict__ Vh, int seq, LAS char* lds, const int wid, f32x16 (&o)[4], float (&rli)[16]) {
;     ...
;     qkt(pA0, pA1, K_lds, qr, negm, r32, hi);
;     partialSM(pA0, pA1, mhat, negm, alA, true); finishSM(pA0, pA1, alA, l_reg, pa0, pa1, pa2, pa3);
;     SWAIT(); SWRITE(1, 1);
;     SLOAD(1, 3 * KVBLK);
;     SWAIT(); SWRITE(2, 0);
;     __syncthreads();
;     if (lag) WBAR();
	ds_read_b128 v[2:5], v0
	ds_read_b128 v[18:21], v0 offset:4096
	v_add_u32_e32 v0, 32, v230
	v_bitop3_b32 v238, v0, v58, s38 bitop3:0x78
	v_add_u32_e32 v0, v241, v238
	ds_read_b128 v[60:63], v0
	s_waitcnt vmcnt(7) lgkmcnt(2)
	v_mfma_f32_32x32x16_bf16 v[2:17], v[2:5], v[156:159], 0
	s_waitcnt lgkmcnt(0)
	v_mfma_f32_32x32x16_bf16 v[2:17], v[60:63], v[152:155], v[2:17]
	ds_read_b128 v[60:63], v0 offset:4096
	v_add_u32_e32 v0, 64, v230
	v_bitop3_b32 v239, v0, v58, s38 bitop3:0x78
	v_add_u32_e32 v0, v241, v239
	v_mfma_f32_32x32x16_bf16 v[18:33], v[18:21], v[156:159], 0
	s_waitcnt lgkmcnt(0)
	v_mfma_f32_32x32x16_bf16 v[18:33], v[60:63], v[152:155], v[18:33]
	ds_read_b128 v[60:63], v0
	s_waitcnt lgkmcnt(0)
	v_mfma_f32_32x32x16_bf16 v[2:17], v[60:63], v[148:151], v[2:17]
	ds_read_b128 v[60:63], v0 offset:4096
	v_add_u32_e32 v0, 0x60, v230
	v_bitop3_b32 v240, v0, v58, s38 bitop3:0x78
	v_add_u32_e32 v0, v241, v240
	s_mov_b32 s38, 0x30000
	s_waitcnt lgkmcnt(0)
	v_mfma_f32_32x32x16_bf16 v[18:33], v[60:63], v[148:151], v[18:33]
	ds_read_b128 v[60:63], v0
	s_waitcnt vmcnt(6) lgkmcnt(0)
	v_mfma_f32_32x32x16_bf16 v[2:17], v[60:63], v[144:147], v[2:17]
	ds_read_b128 v[60:63], v0 offset:4096
	s_waitcnt vmcnt(3)
	s_waitcnt lgkmcnt(0)
	v_mfma_f32_32x32x16_bf16 v[18:33], v[60:63], v[144:147], v[18:33]
	s_nop 8
	v_max_f32_e32 v0, v2, v3
	v_max3_f32 v0, v0, v4, v5
	v_max3_f32 v0, v0, v6, v7
	v_max3_f32 v0, v0, v8, v9
	v_max3_f32 v0, v0, v10, v11
	v_max3_f32 v0, v0, v12, v13
	v_max3_f32 v0, v0, v14, v15
	v_max3_f32 v0, v0, v16, v17
	v_max3_f32 v0, v0, v18, v19
	v_max3_f32 v0, v0, v20, v21
	v_max3_f32 v0, v0, v22, v23
	v_max3_f32 v0, v0, v24, v25
	v_max3_f32 v0, v0, v26, v27
	v_max3_f32 v0, v0, v28, v29
	v_max3_f32 v0, v0, v30, v31
	v_max3_f32 v0, v0, v32, v33
	v_mov_b32_e32 v55, v0
	s_nop 1
	v_permlane32_swap_b32_e32 v0, v55
	v_max_f32_e32 v55, v0, v55
	v_sub_f32_e32 v0, v2, v55
	v_sub_f32_e32 v2, v18, v55
	v_sub_f32_e32 v3, v3, v55
	v_exp_f32_e32 v63, v2
	v_add_co_u32_e32 v2, vcc, s38, v50
	v_sub_f32_e32 v4, v4, v55
	v_exp_f32_e32 v60, v3
	v_addc_co_u32_e32 v3, vcc, 0, v51, vcc
	s_mov_b32 s38, 0x38000
	v_sub_f32_e32 v5, v5, v55
	v_exp_f32_e32 v61, v4
	v_add_co_u32_e32 v4, vcc, s38, v50
	v_exp_f32_e32 v62, v5
	s_nop 0
	v_addc_co_u32_e32 v5, vcc, 0, v51, vcc
	global_load_dwordx4 v[172:175], v[2:3], off
	global_load_dwordx4 v[176:179], v[4:5], off
	v_add_co_u32_e32 v2, vcc, 0xcf30000, v52
	v_sub_f32_e32 v18, v19, v55
	s_nop 0
	v_addc_co_u32_e32 v3, vcc, 0, v53, vcc
	global_load_dwordx4 v[180:183], v[2:3], off
	v_sub_f32_e32 v19, v20, v55
	v_sub_f32_e32 v20, v21, v55
	v_sub_f32_e32 v21, v22, v55
	v_sub_f32_e32 v22, v23, v55
	v_sub_f32_e32 v23, v24, v55
	v_sub_f32_e32 v24, v25, v55
	v_sub_f32_e32 v25, v26, v55
	v_sub_f32_e32 v26, v27, v55
	v_sub_f32_e32 v27, v28, v55
	v_sub_f32_e32 v28, v29, v55
	v_sub_f32_e32 v29, v30, v55
	v_sub_f32_e32 v30, v31, v55
	v_sub_f32_e32 v31, v32, v55
	v_sub_f32_e32 v32, v33, v55
	v_exp_f32_e32 v33, v0
	v_sub_f32_e32 v6, v6, v55
	v_sub_f32_e32 v7, v7, v55
	v_exp_f32_e32 v6, v6
	v_add_f32_e32 v0, 0, v33
	v_sub_f32_e32 v8, v8, v55
	v_exp_f32_e32 v7, v7
	v_add_f32_e32 v0, v60, v0
	v_sub_f32_e32 v9, v9, v55
	v_exp_f32_e32 v8, v8
	v_add_f32_e32 v0, v61, v0
	v_sub_f32_e32 v10, v10, v55
	v_exp_f32_e32 v9, v9
	v_add_f32_e32 v0, v62, v0
	v_sub_f32_e32 v11, v11, v55
	v_exp_f32_e32 v10, v10
	v_add_f32_e32 v0, v6, v0
	v_sub_f32_e32 v12, v12, v55
	v_exp_f32_e32 v11, v11
	v_add_f32_e32 v0, v7, v0
	v_sub_f32_e32 v13, v13, v55
	v_exp_f32_e32 v12, v12
	v_add_f32_e32 v0, v8, v0
	v_sub_f32_e32 v14, v14, v55
	v_exp_f32_e32 v13, v13
	v_add_f32_e32 v0, v9, v0
	v_sub_f32_e32 v15, v15, v55
	v_exp_f32_e32 v14, v14
	v_add_f32_e32 v0, v10, v0
	v_sub_f32_e32 v16, v16, v55
	v_exp_f32_e32 v15, v15
	v_add_f32_e32 v0, v11, v0
	v_sub_f32_e32 v17, v17, v55
	v_exp_f32_e32 v16, v16
	v_add_f32_e32 v0, v12, v0
	v_exp_f32_e32 v17, v17
	v_add_f32_e32 v0, v13, v0
	v_add_f32_e32 v0, v14, v0
	v_exp_f32_e32 v18, v18
	v_add_f32_e32 v0, v15, v0
	v_exp_f32_e32 v19, v19
	v_add_f32_e32 v0, v16, v0
	v_exp_f32_e32 v20, v20
	v_add_f32_e32 v0, v17, v0
	v_exp_f32_e32 v21, v21
	v_add_f32_e32 v0, v63, v0
	v_exp_f32_e32 v22, v22
	v_add_f32_e32 v0, v18, v0
	v_exp_f32_e32 v23, v23
	v_add_f32_e32 v0, v19, v0
	v_exp_f32_e32 v24, v24
	v_add_f32_e32 v0, v20, v0
	v_exp_f32_e32 v25, v25
	v_add_f32_e32 v0, v21, v0
	v_exp_f32_e32 v26, v26
	v_add_f32_e32 v0, v22, v0
	v_exp_f32_e32 v27, v27
	v_add_f32_e32 v0, v23, v0
	v_exp_f32_e32 v28, v28
	v_add_f32_e32 v0, v24, v0
	v_exp_f32_e32 v29, v29
	v_add_f32_e32 v0, v25, v0
	v_exp_f32_e32 v30, v30
	v_add_f32_e32 v0, v26, v0
	v_exp_f32_e32 v31, v31
	v_add_f32_e32 v0, v27, v0
	v_exp_f32_e32 v32, v32
	v_add_f32_e32 v0, v28, v0
	v_add_f32_e32 v0, v29, v0
	v_add_u32_e32 v3, 0, v54
	v_add_f32_e32 v0, v30, v0
	v_add_u32_e32 v4, 0x12000, v3
	v_add_f32_e32 v0, v31, v0
	s_waitcnt vmcnt(8)
	ds_write_b128 v64, v[34:37] offset:16384
	s_waitcnt vmcnt(7)
	ds_write_b128 v65, v[38:41] offset:16384
	s_waitcnt vmcnt(6)
	ds_write_b128 v4, v[42:45]
	v_readlane_b32 s38, v252, 48
	v_add_f32_e32 v0, v32, v0
	s_waitcnt vmcnt(3)
	v_add_u32_e32 v3, 0x14000, v3
	v_readlane_b32 s39, v252, 49
	v_mov_b32_e32 v2, v0
	v_cvt_pk_bf16_f32 v184, v33, v60
	v_cvt_pk_bf16_f32 v185, v61, v62
	v_cvt_pk_bf16_f32 v186, v6, v7
	v_cvt_pk_bf16_f32 v187, v8, v9
	v_cvt_pk_bf16_f32 v188, v10, v11
	v_cvt_pk_bf16_f32 v189, v12, v13
	v_cvt_pk_bf16_f32 v190, v14, v15
	v_cvt_pk_bf16_f32 v191, v16, v17
	v_cvt_pk_bf16_f32 v192, v63, v18
	v_cvt_pk_bf16_f32 v193, v19, v20
	v_cvt_pk_bf16_f32 v194, v21, v22
	v_cvt_pk_bf16_f32 v195, v23, v24
	v_cvt_pk_bf16_f32 v196, v25, v26
	v_cvt_pk_bf16_f32 v197, v27, v28
	v_cvt_pk_bf16_f32 v198, v29, v30
	v_cvt_pk_bf16_f32 v199, v31, v32
	s_waitcnt vmcnt(5)
	ds_write_b128 v64, v[160:163] offset:32768
	s_waitcnt vmcnt(4)
	ds_write_b128 v65, v[164:167] offset:32768
	s_waitcnt vmcnt(3)
	ds_write_b128 v3, v[168:171]
	v_cndmask_b32_e64 v3, 0, 1, s[38:39]
	v_permlane32_swap_b32_e32 v0, v2
	v_permlane32_swap_b32_e32 v184, v186
	v_permlane32_swap_b32_e32 v185, v187
	v_permlane32_swap_b32_e32 v188, v190
	v_permlane32_swap_b32_e32 v189, v191
	v_permlane32_swap_b32_e32 v192, v194
	v_permlane32_swap_b32_e32 v193, v195
	v_permlane32_swap_b32_e32 v196, v198
	v_permlane32_swap_b32_e32 v197, v199
	v_cmp_ne_u32_e64 s[46:47], 1, v3
	s_andn2_b64 vcc, exec, s[38:39]
	s_waitcnt lgkmcnt(0)
	s_barrier
	s_cbranch_vccnz .LBB0_588
	s_waitcnt lgkmcnt(0)
	s_barrier

; __device__ __forceinline__ void partialSM(f32x16& p0, f32x16& p1, float& mhat, f32x16& negm, float& alpha, const bool first) {
;     constexpr float THRL = THR * 1.4426950408889634f;
;     float pmax = p0[0];
; #pragma unroll
;     for (int r = 1; r < 16; ++r) pmax = fmaxf(pmax, p0[r]);
; #pragma unroll
;     for (int r = 0; r < 16; ++r) pmax = fmaxf(pmax, p1[r]);
;     { auto rr = __builtin_amdgcn_permlane32_swap(__float_as_uint(pmax), __float_as_uint(pmax), false, false);
;       pmax = fmaxf(__uint_as_float(rr[0]), __uint_as_float(rr[1])); }
;     if (__builtin_expect(!first && __all(pmax <= THRL), 1)) { alpha = 1.f; }
;     else { const float dl = first ? pmax : fmaxf(pmax, 0.f); mhat += dl; alpha = first ? 0.f : __builtin_amdgcn_exp2f(-dl);
; #pragma unroll
;         for (int r = 0; r < 16; ++r) { p0[r] -= dl; p1[r] -= dl; }
; #pragma unroll
;         for (int r = 0; r < 16; ++r) negm[r] = -mhat; }
.LBB0_593:
	v_max_f32_e32 v0, v128, v129
	v_max3_f32 v0, v0, v130, v131
	v_max3_f32 v0, v0, v132, v133
	v_max3_f32 v0, v0, v134, v135
	v_max3_f32 v0, v0, v136, v137
	v_max3_f32 v0, v0, v138, v139
	v_max3_f32 v0, v0, v140, v141
	v_max3_f32 v0, v0, v142, v143
	v_max3_f32 v0, v0, v112, v113
	v_max3_f32 v0, v0, v114, v115
	v_max3_f32 v0, v0, v116, v117
	v_max3_f32 v0, v0, v118, v119
	v_max3_f32 v0, v0, v120, v121
	v_max3_f32 v0, v0, v122, v123
	v_max3_f32 v0, v0, v124, v125
	v_max3_f32 v0, v0, v126, v127
	v_mov_b32_e32 v2, v0
	s_nop 1
	v_permlane32_swap_b32_e32 v0, v2
	v_max_f32_e32 v0, v0, v2
	v_cmp_ge_f32_e32 vcc, s24, v0
	s_cmp_eq_u64 vcc, exec
	s_cbranch_scc0 .LBB0_606
	v_mov_b32_e32 v0, 1.0
	s_branch .LBB0_598

; __device__ __forceinline__ void partialSM(f32x16& p0, f32x16& p1, float& mhat, f32x16& negm, float& alpha, const bool first) {
;     ...
;     for (int r = 0; r < 16; ++r) p0[r] = __builtin_amdgcn_exp2f(p0[r]);
; }
; __device__ __forceinline__ void finishSM(f32x16& p0, f32x16& p1, float alpha, float& l_reg, bf16x8& pa0, bf16x8& pa1, bf16x8& pa2, bf16x8& pa3) {
; #pragma unroll
;     for (int r = 0; r < 16; ++r) p1[r] = __builtin_amdgcn_exp2f(p1[r]);
;     float ps = 0;
; #pragma unroll
;     for (int r = 0; r < 16; ++r) ps += p0[r];
; #pragma unroll
;     for (int r = 0; r < 16; ++r) ps += p1[r];
;     { auto rr = __builtin_amdgcn_permlane32_swap(__float_as_uint(ps), __float_as_uint(ps), false, false);
;       ps = __uint_as_float(rr[0]) + __uint_as_float(rr[1]); }
;     l_reg = l_reg * alpha + ps;
.LBB0_598:
	v_exp_f32_e32 v2, v128
	v_exp_f32_e32 v3, v129
	v_exp_f32_e32 v4, v130
	v_exp_f32_e32 v5, v131
	v_exp_f32_e32 v6, v132
	v_add_f32_e32 v132, 0, v2
	v_exp_f32_e32 v7, v133
	v_add_f32_e32 v132, v3, v132
	v_exp_f32_e32 v8, v134
	v_add_f32_e32 v132, v4, v132
	v_exp_f32_e32 v9, v135
	v_add_f32_e32 v132, v5, v132
	v_exp_f32_e32 v10, v136
	v_add_f32_e32 v132, v6, v132
	v_exp_f32_e32 v11, v137
	v_add_f32_e32 v132, v7, v132
	v_exp_f32_e32 v12, v138
	v_add_f32_e32 v132, v8, v132
	v_exp_f32_e32 v13, v139
	v_add_f32_e32 v132, v9, v132
	v_exp_f32_e32 v128, v140
	v_add_f32_e32 v132, v10, v132
	v_exp_f32_e32 v129, v141
	v_add_f32_e32 v132, v11, v132
	v_exp_f32_e32 v130, v142
	v_add_f32_e32 v132, v12, v132
	v_exp_f32_e32 v131, v143
	v_add_f32_e32 v132, v13, v132
	v_exp_f32_e32 v112, v112
	v_add_f32_e32 v132, v128, v132
	v_exp_f32_e32 v113, v113
	v_add_f32_e32 v132, v129, v132
	v_exp_f32_e32 v114, v114
	v_add_f32_e32 v132, v130, v132
	v_exp_f32_e32 v115, v115
	v_add_f32_e32 v132, v131, v132
	v_exp_f32_e32 v116, v116
	v_add_f32_e32 v132, v112, v132
	v_exp_f32_e32 v117, v117
	v_add_f32_e32 v132, v113, v132
	v_exp_f32_e32 v118, v118
	v_add_f32_e32 v132, v114, v132
	v_exp_f32_e32 v119, v119
	v_add_f32_e32 v132, v115, v132
	v_exp_f32_e32 v120, v120
	v_add_f32_e32 v132, v116, v132
	v_exp_f32_e32 v121, v121
	v_add_f32_e32 v132, v117, v132
	v_exp_f32_e32 v122, v122
	v_add_f32_e32 v132, v118, v132
	v_exp_f32_e32 v123, v123
	v_add_f32_e32 v132, v119, v132
	v_exp_f32_e32 v124, v124
	v_add_f32_e32 v132, v120, v132
	v_exp_f32_e32 v125, v125
	v_add_f32_e32 v132, v121, v132
	v_exp_f32_e32 v126, v126
	v_add_f32_e32 v132, v122, v132
	v_exp_f32_e32 v127, v127
	v_add_f32_e32 v132, v123, v132
	v_add_f32_e32 v132, v124, v132
	v_add_f32_e32 v132, v125, v132
	v_add_f32_e32 v132, v126, v132
	v_add_f32_e32 v190, v127, v132
	s_waitcnt lgkmcnt(0)
	s_barrier
; #define LAS __attribute__((address_space(3)))
; __device__ __forceinline__ void finishSM(f32x16& p0, f32x16& p1, float alpha, float& l_reg, bf16x8& pa0, bf16x8& pa1, bf16x8& pa2, bf16x8& pa3) {
; #pragma unroll
;     for (int r = 0; r < 16; ++r) p1[r] = __builtin_amdgcn_exp2f(p1[r]);
;     float ps = 0;
; #pragma unroll
;     for (int r = 0; r < 16; ++r) ps += p0[r];
; #pragma unroll
;     for (int r = 0; r < 16; ++r) ps += p1[r];
;     { auto rr = __builtin_amdgcn_permlane32_swap(__float_as_uint(ps), __float_as_uint(ps), false, false);
;       ps = __uint_as_float(rr[0]) + __uint_as_float(rr[1]); }
;     l_reg = l_reg * alpha + ps;
;     ...
;     PK4(p0, 0, pa0); PK4(p0, 8, pa1); PK4(p1, 0, pa2); PK4(p1, 8, pa3);
;     ...
; }
; __device__ __forceinline__ void qkt(f32x16& p0, f32x16& p1, const LAS char* Ks, const bf16x8* qr, const f32x16& negm, int r32, int hi) {
; #pragma unroll
;     for (int d0 = 0; d0 < 4; ++d0) { const int cb = (d0 * 16 + hi * 8) * 2;
;         const bf16x8 b0 = *(const LAS bf16x8*)(Ks + KSWZ(r32, cb));
;         const bf16x8 b1 = *(const LAS bf16x8*)(Ks + KSWZ(32 + r32, cb));
;         if (d0 == 0) { p0 = __builtin_amdgcn_mfma_f32_32x32x16_bf16(b0, qr[0], negm, 0, 0, 0); p1 = __builtin_amdgcn_mfma_f32_32x32x16_bf16(b1, qr[0], negm, 0, 0, 0); }
;         else { p0 = __builtin_amdgcn_mfma_f32_32x32x16_bf16(b0, qr[d0], p0, 0, 0, 0); p1 = __builtin_amdgcn_mfma_f32_32x32x16_bf16(b1, qr[d0], p1, 0, 0, 0); } }
; }
; __device__ __forceinline__ int v_st(int k, int c) { const int kk = (k & ~0xC) | ((k & 4) << 1) | ((k & 8) >> 1); return ((kk >> 3) * 4 + (c >> 5)) * 512 + ((kk & 7) * 32 + (c & 31)) * 2; }
; __device__ __forceinline__ int v_rd_base(int lane) { return ((lane & 3) << 3) | (((lane >> 2) & 3) << 6) | (((lane >> 4) & 1) << 5) | (((lane >> 5) & 1) << 8); }
; template <int OFF> __device__ __forceinline__ s16x4 tr_read(int vb) {
;     s16x4 r; asm volatile("ds_read_b64_tr_b16 %0, %1 offset:%2" : "=&v"(r) : "v"(vb), "i"(OFF) : "memory"); return r;
; }
; template <int D0> __device__ __forceinline__ void pv_one(f32x16& od, int vb, bf16x8 pa0, bf16x8 pa1, bf16x8 pa2, bf16x8 pa3) {
;     const s16x4 l0 = tr_read<v_rd_off(D0, 0, 0)>(vb), h0 = tr_read<v_rd_off(D0, 0, 1)>(vb), l1 = tr_read<v_rd_off(D0, 1, 0)>(vb), h1 = tr_read<v_rd_off(D0, 1, 1)>(vb);
	v_mov_b32_e32 v191, v190
	s_nop 1
	v_permlane32_swap_b32_e32 v190, v191
	v_cvt_pk_bf16_f32 v2, v2, v3
	v_cvt_pk_bf16_f32 v3, v4, v5
	v_cvt_pk_bf16_f32 v4, v6, v7
	v_cvt_pk_bf16_f32 v5, v8, v9
	v_cvt_pk_bf16_f32 v6, v10, v11
	v_cvt_pk_bf16_f32 v7, v12, v13
	v_cvt_pk_bf16_f32 v8, v128, v129
	v_cvt_pk_bf16_f32 v9, v130, v131
	v_cvt_pk_bf16_f32 v10, v112, v113
	v_cvt_pk_bf16_f32 v11, v114, v115
	v_cvt_pk_bf16_f32 v12, v116, v117
	v_cvt_pk_bf16_f32 v13, v118, v119
	v_cvt_pk_bf16_f32 v184, v120, v121
	v_cvt_pk_bf16_f32 v185, v122, v123
	v_cvt_pk_bf16_f32 v186, v124, v125
	v_cvt_pk_bf16_f32 v187, v126, v127
	v_permlane32_swap_b32_e32 v2, v4
	v_permlane32_swap_b32_e32 v3, v5
	v_permlane32_swap_b32_e32 v6, v8
	v_permlane32_swap_b32_e32 v7, v9
	v_permlane32_swap_b32_e32 v10, v12
	v_permlane32_swap_b32_e32 v11, v13
	v_permlane32_swap_b32_e32 v184, v186
	v_permlane32_swap_b32_e32 v185, v187
	s_setprio 1
	s_and_b32 s4, s38, 0x6000
	v_add_u32_e32 v200, s4, v241
	v_add_u32_e32 v112, v200, v237
	ds_read_b128 v[192:195], v112 offset:4096
	ds_read_b128 v[112:115], v112
	v_add_u32_e32 v196, v200, v238
	s_waitcnt lgkmcnt(0)
	v_mfma_f32_32x32x16_bf16 v[128:143], v[112:115], v[156:159], v[96:111]
	v_mfma_f32_32x32x16_bf16 v[112:127], v[192:195], v[156:159], v[96:111]
	ds_read_b128 v[192:195], v196 offset:4096
	ds_read_b128 v[196:199], v196
	s_waitcnt lgkmcnt(1)
	v_mfma_f32_32x32x16_bf16 v[112:127], v[192:195], v[152:155], v[112:127]
	s_waitcnt lgkmcnt(0)
	v_mfma_f32_32x32x16_bf16 v[128:143], v[196:199], v[152:155], v[128:143]
	v_add_u32_e32 v196, v200, v239
	ds_read_b128 v[192:195], v196 offset:4096
	ds_read_b128 v[196:199], v196
	s_waitcnt lgkmcnt(1)
	v_mfma_f32_32x32x16_bf16 v[112:127], v[192:195], v[148:151], v[112:127]
	s_waitcnt lgkmcnt(0)
	v_mfma_f32_32x32x16_bf16 v[128:143], v[196:199], v[148:151], v[128:143]
	v_add_u32_e32 v196, v200, v240
	ds_read_b128 v[192:195], v196 offset:4096
	ds_read_b128 v[196:199], v196
	v_lshl_add_u32 v200, s61, 14, v242
	ds_read_b64_tr_b16 v[172:173], v200 offset:0
	ds_read_b64_tr_b16 v[174:175], v200 offset:0x800
	ds_read_b64_tr_b16 v[176:177], v200 offset:0x1000
	ds_read_b64_tr_b16 v[178:179], v200 offset:0x1800
	s_waitcnt lgkmcnt(5)
	v_mfma_f32_32x32x16_bf16 v[112:127], v[192:195], v[144:147], v[112:127]
	ds_read_b64_tr_b16 v[220:221], v200 offset:0x2000
	ds_read_b64_tr_b16 v[222:223], v200 offset:0x2800
	s_waitcnt lgkmcnt(6)
	v_mfma_f32_32x32x16_bf16 v[128:143], v[196:199], v[144:147], v[128:143]
	ds_read_b64_tr_b16 v[244:245], v200 offset:0x3000
	ds_read_b64_tr_b16 v[246:247], v200 offset:0x3800
	s_waitcnt lgkmcnt(6)
	v_mfma_f32_32x32x16_bf16 v[64:79], v[2:5], v[172:175], v[64:79]
	ds_read_b64_tr_b16 v[192:193], v200 offset:0x200
	ds_read_b64_tr_b16 v[194:195], v200 offset:0xa00
	s_waitcnt lgkmcnt(6)
	v_mfma_f32_32x32x16_bf16 v[64:79], v[6:9], v[176:179], v[64:79]
	ds_read_b64_tr_b16 v[196:197], v200 offset:0x1200
	ds_read_b64_tr_b16 v[198:199], v200 offset:0x1a00
	s_waitcnt lgkmcnt(6)
	v_mfma_f32_32x32x16_bf16 v[64:79], v[10:13], v[220:223], v[64:79]
	ds_read_b64_tr_b16 v[220:221], v200 offset:0x2200
	ds_read_b64_tr_b16 v[222:223], v200 offset:0x2a00
	s_waitcnt lgkmcnt(6)
	v_mfma_f32_32x32x16_bf16 v[64:79], v[184:187], v[244:247], v[64:79]
	ds_read_b64_tr_b16 v[244:245], v200 offset:0x3200
	ds_read_b64_tr_b16 v[246:247], v200 offset:0x3a00
	s_waitcnt lgkmcnt(6)
	v_mfma_f32_32x32x16_bf16 v[48:63], v[2:5], v[192:195], v[48:63]
	ds_read_b64_tr_b16 v[192:193], v200 offset:0x400
	ds_read_b64_tr_b16 v[194:195], v200 offset:0xc00
	s_waitcnt lgkmcnt(6)
	v_mfma_f32_32x32x16_bf16 v[48:63], v[6:9], v[196:199], v[48:63]
	ds_read_b64_tr_b16 v[196:197], v200 offset:0x1400
	ds_read_b64_tr_b16 v[198:199], v200 offset:0x1c00
	s_waitcnt lgkmcnt(6)
	v_mfma_f32_32x32x16_bf16 v[48:63], v[10:13], v[220:223], v[48:63]
	ds_read_b64_tr_b16 v[220:221], v200 offset:0x2400
	ds_read_b64_tr_b16 v[222:223], v200 offset:0x2c00
	s_waitcnt lgkmcnt(6)
	v_mfma_f32_32x32x16_bf16 v[48:63], v[184:187], v[244:247], v[48:63]
	ds_read_b64_tr_b16 v[244:245], v200 offset:0x3400
	ds_read_b64_tr_b16 v[246:247], v200 offset:0x3c00
	s_waitcnt lgkmcnt(6)
	v_mfma_f32_32x32x16_bf16 v[32:47], v[2:5], v[192:195], v[32:47]
	ds_read_b64_tr_b16 v[192:193], v200 offset:0x600
	ds_read_b64_tr_b16 v[194:195], v200 offset:0xe00
	s_waitcnt lgkmcnt(6)
	v_mfma_f32_32x32x16_bf16 v[32:47], v[6:9], v[196:199], v[32:47]
	ds_read_b64_tr_b16 v[196:197], v200 offset:0x1600
	ds_read_b64_tr_b16 v[198:199], v200 offset:0x1e00
	s_waitcnt lgkmcnt(6)
	v_mfma_f32_32x32x16_bf16 v[32:47], v[10:13], v[220:223], v[32:47]
	ds_read_b64_tr_b16 v[220:221], v200 offset:0x2600
	ds_read_b64_tr_b16 v[222:223], v200 offset:0x2e00
	s_waitcnt lgkmcnt(6)
	v_mfma_f32_32x32x16_bf16 v[32:47], v[184:187], v[244:247], v[32:47]
	ds_read_b64_tr_b16 v[244:245], v200 offset:0x3600
	ds_read_b64_tr_b16 v[246:247], v200 offset:0x3e00
	s_waitcnt lgkmcnt(6)
	v_mfma_f32_32x32x16_bf16 v[16:31], v[2:5], v[192:195], v[16:31]
	s_waitcnt lgkmcnt(4)
	v_mfma_f32_32x32x16_bf16 v[16:31], v[6:9], v[196:199], v[16:31]
	s_waitcnt lgkmcnt(2)
	v_mfma_f32_32x32x16_bf16 v[16:31], v[10:13], v[220:223], v[16:31]
	s_waitcnt lgkmcnt(0)
	v_mfma_f32_32x32x16_bf16 v[16:31], v[184:187], v[244:247], v[16:31]
	s_setprio 0
	s_waitcnt lgkmcnt(0)
	s_barrier
	s_andn2_b64 vcc, exec, s[2:3]
	s_cbranch_vccnz .LBB0_600
	s_and_b32 s2, s49, 3
	s_lshl_b32 s3, s2, 14
	s_add_i32 s3, s3, 0
	v_add_u32_e32 v2, s3, v233
	v_add_u32_e32 v3, s3, v234
	v_lshl_add_u32 v4, s2, 13, v235
	s_waitcnt vmcnt(2)
	ds_write_b128 v2, v[160:163]
	s_waitcnt vmcnt(1)
	ds_write_b128 v3, v[164:167]
	s_waitcnt vmcnt(0)
	ds_write_b128 v4, v[168:171]

; __device__ __forceinline__ void partialSM(f32x16& p0, f32x16& p1, float& mhat, f32x16& negm, float& alpha, const bool first) {
;     constexpr float THRL = THR * 1.4426950408889634f;
;     float pmax = p0[0];
; #pragma unroll
;     for (int r = 1; r < 16; ++r) pmax = fmaxf(pmax, p0[r]);
; #pragma unroll
;     for (int r = 0; r < 16; ++r) pmax = fmaxf(pmax, p1[r]);
;     { auto rr = __builtin_amdgcn_permlane32_swap(__float_as_uint(pmax), __float_as_uint(pmax), false, false);
;       pmax = fmaxf(__uint_as_float(rr[0]), __uint_as_float(rr[1])); }
;     if (__builtin_expect(!first && __all(pmax <= THRL), 1)) { alpha = 1.f; }
;     else { const float dl = first ? pmax : fmaxf(pmax, 0.f); mhat += dl; alpha = first ? 0.f : __builtin_amdgcn_exp2f(-dl);
; #pragma unroll
;         for (int r = 0; r < 16; ++r) { p0[r] -= dl; p1[r] -= dl; }
; #pragma unroll
;         for (int r = 0; r < 16; ++r) negm[r] = -mhat; }
.LBB0_602:
	v_max_f32_e32 v2, v128, v129
	v_max3_f32 v2, v2, v130, v131
	v_max3_f32 v2, v2, v132, v133
	v_max3_f32 v2, v2, v134, v135
	v_max3_f32 v2, v2, v136, v137
	v_max3_f32 v2, v2, v138, v139
	v_max3_f32 v2, v2, v140, v141
	v_max3_f32 v2, v2, v142, v143
	v_max3_f32 v2, v2, v112, v113
	v_max3_f32 v2, v2, v114, v115
	v_max3_f32 v2, v2, v116, v117
	v_max3_f32 v2, v2, v118, v119
	v_max3_f32 v2, v2, v120, v121
	v_max3_f32 v2, v2, v122, v123
	v_max3_f32 v2, v2, v124, v125
	v_max3_f32 v2, v2, v126, v127
	v_mov_b32_e32 v3, v2
	s_nop 1
	v_permlane32_swap_b32_e32 v2, v3
	v_max_f32_e32 v3, v2, v3
	v_cmp_ge_f32_e32 vcc, s24, v3
	s_cmp_eq_u64 vcc, exec
	v_mov_b32_e32 v2, 1.0
	s_cbranch_scc0 .LBB0_607
	s_branch .LBB0_590

; #define LAS __attribute__((address_space(3)))
; #define SBAR() __builtin_amdgcn_sched_barrier(0)
; __device__ __forceinline__ void qkt(f32x16& p0, f32x16& p1, const LAS char* Ks, const bf16x8* qr, const f32x16& negm, int r32, int hi) {
; #pragma unroll
;     for (int d0 = 0; d0 < 4; ++d0) { const int cb = (d0 * 16 + hi * 8) * 2;
;         const bf16x8 b0 = *(const LAS bf16x8*)(Ks + KSWZ(r32, cb));
;         const bf16x8 b1 = *(const LAS bf16x8*)(Ks + KSWZ(32 + r32, cb));
;         if (d0 == 0) { p0 = __builtin_amdgcn_mfma_f32_32x32x16_bf16(b0, qr[0], negm, 0, 0, 0); p1 = __builtin_amdgcn_mfma_f32_32x32x16_bf16(b1, qr[0], negm, 0, 0, 0); }
;         else { p0 = __builtin_amdgcn_mfma_f32_32x32x16_bf16(b0, qr[d0], p0, 0, 0, 0); p1 = __builtin_amdgcn_mfma_f32_32x32x16_bf16(b1, qr[d0], p1, 0, 0, 0); } }
; }
; __device__ __forceinline__ int v_st(int k, int c) { const int kk = (k & ~0xC) | ((k & 4) << 1) | ((k & 8) >> 1); return ((kk >> 3) * 4 + (c >> 5)) * 512 + ((kk & 7) * 32 + (c & 31)) * 2; }
; __device__ __forceinline__ int v_rd_base(int lane) { return ((lane & 3) << 3) | (((lane >> 2) & 3) << 6) | (((lane >> 4) & 1) << 5) | (((lane >> 5) & 1) << 8); }
; template <int OFF> __device__ __forceinline__ s16x4 tr_read(int vb) {
;     s16x4 r; asm volatile("ds_read_b64_tr_b16 %0, %1 offset:%2" : "=&v"(r) : "v"(vb), "i"(OFF) : "memory"); return r;
; }
; template <int D0> __device__ __forceinline__ void pv_one(f32x16& od, int vb, bf16x8 pa0, bf16x8 pa1, bf16x8 pa2, bf16x8 pa3) {
;     const s16x4 l0 = tr_read<v_rd_off(D0, 0, 0)>(vb), h0 = tr_read<v_rd_off(D0, 0, 1)>(vb), l1 = tr_read<v_rd_off(D0, 1, 0)>(vb), h1 = tr_read<v_rd_off(D0, 1, 1)>(vb);
;     const s16x4 l2 = tr_read<v_rd_off(D0, 2, 0)>(vb), h2 = tr_read<v_rd_off(D0, 2, 1)>(vb), l3 = tr_read<v_rd_off(D0, 3, 0)>(vb), h3 = tr_read<v_rd_off(D0, 3, 1)>(vb);
;     asm volatile("s_waitcnt lgkmcnt(0)" ::: "memory"); SBAR();
;     ...
;     od = __builtin_amdgcn_mfma_f32_32x32x16_bf16(pa0, PK(l0, h0), od, 0, 0, 0);
;     od = __builtin_amdgcn_mfma_f32_32x32x16_bf16(pa1, PK(l1, h1), od, 0, 0, 0);
;     od = __builtin_amdgcn_mfma_f32_32x32x16_bf16(pa2, PK(l2, h2), od, 0, 0, 0);
;     od = __builtin_amdgcn_mfma_f32_32x32x16_bf16(pa3, PK(l3, h3), od, 0, 0, 0);
;     ...
; }
; __device__ __forceinline__ void pv_d0(f32x16* o, int vb, bf16x8 pa0, bf16x8 pa1, bf16x8 pa2, bf16x8 pa3) {
.LBB0_608:
	v_mov_b64_e32 v[80:81], v[96:97]
	v_mov_b64_e32 v[82:83], v[98:99]
	v_mov_b64_e32 v[84:85], v[100:101]
	v_mov_b64_e32 v[86:87], v[102:103]
	v_mov_b64_e32 v[88:89], v[104:105]
	v_mov_b64_e32 v[90:91], v[106:107]
	v_mov_b64_e32 v[92:93], v[108:109]
	v_mov_b64_e32 v[94:95], v[110:111]
	s_setprio 1
	s_add_i32 s61, 0, 0x16000
	v_add_u32_e32 v0, s61, v236
	v_add_u32_e32 v6, v0, v237
	ds_read_b128 v[2:5], v6
	s_add_i32 s62, 0, 0x8000
	s_waitcnt lgkmcnt(0)
	v_mfma_f32_32x32x16_bf16 v[96:111], v[2:5], v[156:159], v[80:95]
	ds_read_b128 v[2:5], v6 offset:4096
	v_add_u32_e32 v6, v0, v238
	s_waitcnt lgkmcnt(0)
	v_mfma_f32_32x32x16_bf16 v[80:95], v[2:5], v[156:159], v[80:95]
	ds_read_b128 v[2:5], v6
	s_waitcnt lgkmcnt(0)
	v_mfma_f32_32x32x16_bf16 v[96:111], v[2:5], v[152:155], v[96:111]
	ds_read_b128 v[2:5], v6 offset:4096
	v_add_u32_e32 v6, v0, v239
	v_add_u32_e32 v0, v0, v240
	s_waitcnt lgkmcnt(0)
	v_mfma_f32_32x32x16_bf16 v[80:95], v[2:5], v[152:155], v[80:95]
	ds_read_b128 v[2:5], v6
	s_waitcnt lgkmcnt(0)
	v_mfma_f32_32x32x16_bf16 v[96:111], v[2:5], v[148:151], v[96:111]
	ds_read_b128 v[2:5], v6 offset:4096
	s_waitcnt lgkmcnt(0)
	v_mfma_f32_32x32x16_bf16 v[80:95], v[2:5], v[148:151], v[80:95]
	ds_read_b128 v[2:5], v0
	ds_read_b128 v[6:9], v0 offset:4096
	v_add_u32_e32 v0, s62, v232
	ds_read_b64_tr_b16 v[10:11], v0 offset:0
	ds_read_b64_tr_b16 v[12:13], v0 offset:0x800
	s_waitcnt lgkmcnt(1)
	v_mfma_f32_32x32x16_bf16 v[96:111], v[2:5], v[144:147], v[96:111]
	ds_read_b64_tr_b16 v[2:3], v0 offset:0x1000
	ds_read_b64_tr_b16 v[4:5], v0 offset:0x1800
	ds_read_b64_tr_b16 v[112:113], v0 offset:0x2000
	ds_read_b64_tr_b16 v[114:115], v0 offset:0x2800
	ds_read_b64_tr_b16 v[116:117], v0 offset:0x3000
	ds_read_b64_tr_b16 v[118:119], v0 offset:0x3800
	s_waitcnt lgkmcnt(0)
	s_waitcnt lgkmcnt(0)
	v_mfma_f32_32x32x16_bf16 v[80:95], v[6:9], v[144:147], v[80:95]
	v_mfma_f32_32x32x16_bf16 v[64:79], v[184:187], v[10:13], v[64:79]
	v_mfma_f32_32x32x16_bf16 v[64:79], v[188:191], v[2:5], v[64:79]
	ds_read_b64_tr_b16 v[2:3], v0 offset:0x200
	ds_read_b64_tr_b16 v[4:5], v0 offset:0xa00
	ds_read_b64_tr_b16 v[6:7], v0 offset:0x1200
	ds_read_b64_tr_b16 v[8:9], v0 offset:0x1a00
	ds_read_b64_tr_b16 v[10:11], v0 offset:0x2200
	ds_read_b64_tr_b16 v[12:13], v0 offset:0x2a00
	v_mfma_f32_32x32x16_bf16 v[64:79], v[192:195], v[112:115], v[64:79]
	ds_read_b64_tr_b16 v[112:113], v0 offset:0x3200
	ds_read_b64_tr_b16 v[114:115], v0 offset:0x3a00
	s_waitcnt lgkmcnt(0)
	v_mfma_f32_32x32x16_bf16 v[64:79], v[196:199], v[116:119], v[64:79]
	v_mfma_f32_32x32x16_bf16 v[48:63], v[184:187], v[2:5], v[48:63]
	ds_read_b64_tr_b16 v[2:3], v0 offset:0x400
	ds_read_b64_tr_b16 v[4:5], v0 offset:0xc00
	v_mfma_f32_32x32x16_bf16 v[48:63], v[188:191], v[6:9], v[48:63]
	ds_read_b64_tr_b16 v[6:7], v0 offset:0x1400
	ds_read_b64_tr_b16 v[8:9], v0 offset:0x1c00
	v_mfma_f32_32x32x16_bf16 v[48:63], v[192:195], v[10:13], v[48:63]
	ds_read_b64_tr_b16 v[10:11], v0 offset:0x2400
	ds_read_b64_tr_b16 v[12:13], v0 offset:0x2c00
	v_mfma_f32_32x32x16_bf16 v[48:63], v[196:199], v[112:115], v[48:63]
	ds_read_b64_tr_b16 v[112:113], v0 offset:0x3400
	ds_read_b64_tr_b16 v[114:115], v0 offset:0x3c00
	s_waitcnt lgkmcnt(0)
	v_mfma_f32_32x32x16_bf16 v[32:47], v[184:187], v[2:5], v[32:47]
	ds_read_b64_tr_b16 v[2:3], v0 offset:0x600
	ds_read_b64_tr_b16 v[4:5], v0 offset:0xe00
	v_mfma_f32_32x32x16_bf16 v[32:47], v[188:191], v[6:9], v[32:47]
	ds_read_b64_tr_b16 v[6:7], v0 offset:0x1600
	ds_read_b64_tr_b16 v[8:9], v0 offset:0x1e00
	v_mfma_f32_32x32x16_bf16 v[32:47], v[192:195], v[10:13], v[32:47]
	ds_read_b64_tr_b16 v[10:11], v0 offset:0x2600
	ds_read_b64_tr_b16 v[12:13], v0 offset:0x2e00
	v_mfma_f32_32x32x16_bf16 v[32:47], v[196:199], v[112:115], v[32:47]
	ds_read_b64_tr_b16 v[112:113], v0 offset:0x3600
	ds_read_b64_tr_b16 v[114:115], v0 offset:0x3e00
	s_waitcnt lgkmcnt(0)
	v_mfma_f32_32x32x16_bf16 v[16:31], v[184:187], v[2:5], v[16:31]
	v_mfma_f32_32x32x16_bf16 v[16:31], v[188:191], v[6:9], v[16:31]
	v_mfma_f32_32x32x16_bf16 v[16:31], v[192:195], v[10:13], v[16:31]
	v_mfma_f32_32x32x16_bf16 v[16:31], v[196:199], v[112:115], v[16:31]
	s_setprio 0
	v_max_f32_e32 v0, v96, v97
	v_max3_f32 v0, v0, v98, v99
	v_max3_f32 v0, v0, v100, v101
	v_max3_f32 v0, v0, v102, v103
	v_max3_f32 v0, v0, v104, v105
	v_max3_f32 v0, v0, v106, v107
	v_max3_f32 v0, v0, v108, v109
	v_max3_f32 v0, v0, v110, v111
	v_max3_f32 v0, v0, v80, v81
	v_max3_f32 v0, v0, v82, v83
	v_max3_f32 v0, v0, v84, v85
	v_max3_f32 v0, v0, v86, v87
	v_max3_f32 v0, v0, v88, v89
	v_max3_f32 v0, v0, v90, v91
	v_max3_f32 v0, v0, v92, v93
	v_max3_f32 v0, v0, v94, v95
	v_mov_b32_e32 v2, v0
	s_nop 1
	v_permlane32_swap_b32_e32 v0, v2
	v_max_f32_e32 v2, v2, v2
	v_max_f32_e32 v0, v0, v0
	s_waitcnt lgkmcnt(0)
	s_barrier
	v_max_f32_e32 v2, v0, v2
	v_cmp_ge_f32_e32 vcc, s24, v2
	s_cmp_eq_u64 vcc, exec
	v_mov_b32_e32 v0, 1.0
	s_cbranch_scc0 .LBB0_648
	v_cmp_gt_f32_e32 vcc, 1.0, v0
	s_cbranch_vccz .LBB0_613

; #define LAS __attribute__((address_space(3)))
; __device__ __forceinline__ int fresh_lane() { int l; asm volatile("v_mbcnt_lo_u32_b32 %0, -1, 0\n\tv_mbcnt_hi_u32_b32 %0, -1, %0" : "=v"(l)); return l; }
; __device__ __forceinline__ int crow(int r, int hi) { return (r & 3) + 8 * (r >> 2) + 4 * hi; }
; __device__ __forceinline__ void attn_pass(const bf16_t* __restrict__ Qb, const bf16_t* __restrict__ Kh, const bf16_t* __restrict__ Vh, int seq, LAS char* lds, const int wid, f32x16 (&o)[4], float (&rli)[16]) {
;     ...
;     if (hi == 0) li_l[r32] = l_reg; asm volatile("s_waitcnt lgkmcnt(0)" ::: "memory");
; #pragma unroll
;     for (int r = 0; r < 16; ++r) rli[r] = __builtin_amdgcn_rcpf(li_l[crow(r, hi)]);
;     asm volatile("s_waitcnt vmcnt(0) lgkmcnt(0)" ::: "memory");
;     __syncthreads();
; __global__ void __launch_bounds__(NTHREADS, 2) mega(Args a) {
;     ...
;                     {
;                         f32x4* p = (f32x4*)STASH + (size_t)wave * 1024 + (fresh_lane());
; #pragma unroll
;                         for (int d0 = 0; d0 < 4; ++d0)
; #pragma unroll
;                             for (int r4 = 0; r4 < 4; ++r4) {
;                                 f32x4 v; v[0] = o[d0][4 * r4] * rli[4 * r4]; v[1] = o[d0][4 * r4 + 1] * rli[4 * r4 + 1]; v[2] = o[d0][4 * r4 + 2] * rli[4 * r4 + 2]; v[3] = o[d0][4 * r4 + 3] * rli[4 * r4 + 3];
;                                 p[(d0 * 4 + r4) * 64] = v; }
;                     }
;                     att::attn_pass(Qb + row0 * 512 + h * 128 + 64, Kb + (size_t)b * L * 512 + h * 128 + 64, Vb + (size_t)b * L * 512 + h * 128, L, (LAS char*)lds, wave, o, rli);
.LBB0_615:
	s_and_saveexec_b64 s[2:3], s[50:51]
	v_add_f32_e32 v2, v2, v3
	v_fmac_f32_e32 v2, v214, v0
	ds_write_b32 v231, v2
	s_or_b64 exec, exec, s[2:3]
	s_waitcnt lgkmcnt(0)
	v_add_u32_e32 v0, s1, v230
	ds_read_b128 v[2:5], v0
	ds_read_b128 v[6:9], v0 offset:32
	s_mov_b64 s[2:3], s[96:97]
	v_readlane_b32 s4, v253, 52
	v_readlane_b32 s5, v253, 53
	s_waitcnt lgkmcnt(1)
	v_rcp_f32_e32 v10, v2
	v_rcp_f32_e32 v11, v3
	v_rcp_f32_e32 v12, v4
	v_rcp_f32_e32 v13, v5
	ds_read_b128 v[2:5], v0 offset:64
	s_waitcnt lgkmcnt(1)
	v_rcp_f32_e32 v14, v6
	v_rcp_f32_e32 v15, v7
	v_rcp_f32_e32 v80, v8
	v_rcp_f32_e32 v81, v9
	ds_read_b128 v[6:9], v0 offset:96
	s_waitcnt vmcnt(0) lgkmcnt(0)
	s_waitcnt lgkmcnt(0)
	s_barrier
	s_add_u32 s2, s2, s4
	s_addc_u32 s3, s3, s5
	v_readlane_b32 s4, v253, 54
	v_readlane_b32 s5, v253, 55
	s_add_u32 s2, s2, s4
	v_rcp_f32_e32 v82, v2
	v_rcp_f32_e32 v83, v3
	s_addc_u32 s3, s3, s5
	v_mbcnt_lo_u32_b32 v2, -1, 0
	v_mbcnt_hi_u32_b32 v2, -1, v2
	v_rcp_f32_e32 v84, v4
	v_ashrrev_i32_e32 v3, 31, v2
	v_lshl_add_u64 v[86:87], v[2:3], 4, s[2:3]
	s_mov_b64 s[2:3], 0x2f00000
	v_rcp_f32_e32 v85, v5
	v_lshl_add_u64 v[88:89], v[86:87], 0, s[2:3]
	s_mov_b32 s2, 0x2f01000
	v_rcp_f32_e32 v6, v6
	v_rcp_f32_e32 v7, v7
	v_rcp_f32_e32 v8, v8
	v_rcp_f32_e32 v9, v9
	v_pk_mul_f32 v[2:3], v[10:11], v[64:65]
	v_add_co_u32_e32 v64, vcc, s2, v86
	v_pk_mul_f32 v[4:5], v[12:13], v[66:67]
	s_nop 0
	v_addc_co_u32_e32 v65, vcc, 0, v87, vcc
	global_store_dwordx4 v[64:65], v[2:5], off offset:-4096
	s_mov_b32 s2, 0x2f02000
	s_lshl_b64 s[4:5], s[40:41], 1
	v_pk_mul_f32 v[2:3], v[14:15], v[68:69]
	v_pk_mul_f32 v[4:5], v[80:81], v[70:71]
	global_store_dwordx4 v[88:89], v[2:5], off offset:1024
	v_readlane_b32 s50, v252, 23
	s_nop 0
	v_pk_mul_f32 v[2:3], v[82:83], v[72:73]
	v_pk_mul_f32 v[4:5], v[84:85], v[74:75]
	global_store_dwordx4 v[88:89], v[2:5], off offset:2048
	s_nop 1
	v_pk_mul_f32 v[2:3], v[6:7], v[76:77]
	v_pk_mul_f32 v[4:5], v[8:9], v[78:79]
	global_store_dwordx4 v[88:89], v[2:5], off offset:3072
	s_nop 1
	v_pk_mul_f32 v[2:3], v[10:11], v[48:49]
	v_pk_mul_f32 v[4:5], v[12:13], v[50:51]
	global_store_dwordx4 v[64:65], v[2:5], off
	s_nop 1
	v_pk_mul_f32 v[2:3], v[14:15], v[52:53]
	v_pk_mul_f32 v[4:5], v[80:81], v[54:55]
	global_store_dwordx4 v[64:65], v[2:5], off offset:1024
	s_nop 1
	v_pk_mul_f32 v[2:3], v[82:83], v[56:57]
	v_pk_mul_f32 v[4:5], v[84:85], v[58:59]
	global_store_dwordx4 v[64:65], v[2:5], off offset:2048
	s_nop 1
	v_pk_mul_f32 v[2:3], v[6:7], v[60:61]
	v_pk_mul_f32 v[4:5], v[8:9], v[62:63]
	global_store_dwordx4 v[64:65], v[2:5], off offset:3072
	s_nop 1
	v_pk_mul_f32 v[2:3], v[10:11], v[32:33]
	v_add_co_u32_e32 v32, vcc, s2, v86
	s_mov_b32 s2, 0x2f03000
	s_nop 0
	v_addc_co_u32_e32 v33, vcc, 0, v87, vcc
	v_pk_mul_f32 v[4:5], v[12:13], v[34:35]
	v_add_co_u32_e32 v34, vcc, s2, v86
	s_mov_b64 s[2:3], s[96:97]
	s_nop 0
	v_addc_co_u32_e32 v35, vcc, 0, v87, vcc
	global_store_dwordx4 v[34:35], v[2:5], off offset:-4096
	s_nop 1
	v_pk_mul_f32 v[2:3], v[14:15], v[36:37]
	v_pk_mul_f32 v[4:5], v[80:81], v[38:39]
	global_store_dwordx4 v[32:33], v[2:5], off offset:1024
	s_nop 1
	v_pk_mul_f32 v[2:3], v[82:83], v[40:41]
	v_pk_mul_f32 v[4:5], v[84:85], v[42:43]
	global_store_dwordx4 v[32:33], v[2:5], off offset:2048
	s_nop 1
	v_pk_mul_f32 v[2:3], v[6:7], v[44:45]
	v_pk_mul_f32 v[4:5], v[8:9], v[46:47]
	global_store_dwordx4 v[32:33], v[2:5], off offset:3072
	s_nop 1
	v_pk_mul_f32 v[2:3], v[10:11], v[16:17]
	v_pk_mul_f32 v[4:5], v[12:13], v[18:19]
	global_store_dwordx4 v[34:35], v[2:5], off
	s_nop 1
	v_pk_mul_f32 v[2:3], v[14:15], v[20:21]
	v_pk_mul_f32 v[4:5], v[80:81], v[22:23]
	global_store_dwordx4 v[34:35], v[2:5], off offset:1024
	v_mov_b32_e32 v23, v1
	s_nop 0
	v_pk_mul_f32 v[2:3], v[82:83], v[24:25]
	v_pk_mul_f32 v[4:5], v[84:85], v[26:27]
	global_store_dwordx4 v[34:35], v[2:5], off offset:2048
	s_nop 1
	v_pk_mul_f32 v[2:3], v[6:7], v[28:29]
	v_pk_mul_f32 v[4:5], v[8:9], v[30:31]
	global_store_dwordx4 v[34:35], v[2:5], off offset:3072
	s_add_u32 s2, s2, s4
	s_addc_u32 s3, s3, s5
	s_add_u32 s38, s2, s84
	s_addc_u32 s39, s3, 0
	s_mov_b64 s[2:3], s[96:97]
	s_lshl_b64 s[34:35], s[34:35], 1
	s_add_u32 s4, s2, s34
	s_addc_u32 s5, s3, s35
	s_add_u32 s40, s4, s84
	s_addc_u32 s41, s5, 0
	s_mov_b64 s[4:5], s[96:97]
	s_add_u32 s34, s4, s34
	s_addc_u32 s35, s5, s35
	s_add_u32 s34, s34, s84
	v_mbcnt_lo_u32_b32 v56, -1, 0
	v_mbcnt_hi_u32_b32 v56, -1, v56
	s_addc_u32 s35, s35, 0
	v_add_u32_e32 v26, s25, v56
	v_and_b32_e32 v57, 31, v56
	v_ashrrev_i32_e32 v16, 4, v26
	s_add_u32 s34, s34, 0xef00000
	v_or_b32_e32 v0, s50, v57
	v_lshlrev_b32_e32 v58, 3, v56
	v_ashrrev_i32_e32 v17, 31, v16
	s_addc_u32 s35, s35, 0
	v_lshlrev_b64 v[14:15], 10, v[0:1]
	v_and_b32_e32 v0, 0x78, v58
	v_add_u32_e32 v18, 32, v16
	v_ashrrev_i32_e32 v20, 3, v26
	v_lshlrev_b64 v[46:47], 10, v[16:17]
	v_lshl_add_u64 v[2:3], s[34:35], 0, v[46:47]
	v_lshlrev_b32_e32 v0, 1, v0
	v_ashrrev_i32_e32 v19, 31, v18
	v_ashrrev_i32_e32 v21, 31, v20
	v_lshlrev_b32_e32 v59, 4, v56
	v_lshl_add_u64 v[50:51], v[2:3], 0, v[0:1]
	v_lshlrev_b64 v[2:3], 10, v[18:19]
	v_lshlrev_b64 v[48:49], 10, v[20:21]
	v_and_b32_e32 v22, 0x70, v59
	v_lshl_add_u64 v[2:3], s[34:35], 0, v[2:3]
	v_lshl_add_u64 v[10:11], s[40:41], 0, v[48:49]
	v_lshl_add_u64 v[6:7], v[2:3], 0, v[0:1]
	v_lshl_add_u64 v[52:53], v[10:11], 0, v[22:23]
	s_mov_b32 s34, 0xcf00000
	global_load_dwordx4 v[2:5], v[50:51], off
	s_nop 0
	global_load_dwordx4 v[6:9], v[6:7], off
	v_add_co_u32_e32 v10, vcc, s34, v52
	v_ashrrev_i32_e32 v0, 5, v56
	s_nop 0
	v_addc_co_u32_e32 v11, vcc, 0, v53, vcc
	global_load_dwordx4 v[10:13], v[10:11], off offset:128
	v_lshlrev_b32_e32 v24, 3, v0
	v_lshl_add_u64 v[14:15], s[38:39], 0, v[14:15]
	v_ashrrev_i32_e32 v25, 31, v24
	v_lshl_add_u64 v[14:15], v[24:25], 1, v[14:15]
	s_mov_b64 s[34:35], 0xaf00080
	s_mov_b32 s39, 0xaf00000
	v_lshl_add_u64 v[24:25], v[14:15], 0, s[34:35]
	v_add_co_u32_e32 v14, vcc, s39, v14
	v_bfe_u32 v17, v58, 5, 2
	s_nop 0
	v_addc_co_u32_e32 v15, vcc, 0, v15, vcc
	global_load_dwordx4 v[156:159], v[14:15], off offset:128
	global_load_dwordx4 v[152:155], v[24:25], off offset:32
	global_load_dwordx4 v[148:151], v[24:25], off offset:64
	global_load_dwordx4 v[144:147], v[24:25], off offset:96
	v_and_b32_e32 v14, 0xfffff0, v16
	v_lshlrev_b32_e32 v15, 1, v16
	v_and_or_b32 v14, v15, 8, v14
	v_lshrrev_b32_e32 v15, 1, v16
	v_lshrrev_b32_e32 v14, 1, v14
	v_and_b32_e32 v16, 3, v16
	v_or_b32_e32 v14, v14, v17
	v_and_or_b32 v15, v15, 4, v16
	v_lshlrev_b32_e32 v14, 9, v14
	v_lshlrev_b32_e32 v15, 6, v15
	v_and_b32_e32 v16, 48, v59
	v_or3_b32 v233, v14, v15, v16
	v_and_b32_e32 v14, 0xfffff0, v18
	v_lshlrev_b32_e32 v18, 1, v18
	v_and_or_b32 v14, v18, 8, v14
	v_lshrrev_b32_e32 v14, 1, v14
	v_or_b32_e32 v14, v14, v17
	v_lshlrev_b32_e32 v14, 9, v14
	v_add_u32_e32 v68, 0, v233
	s_mov_b32 s34, 0x10000
	v_or3_b32 v234, v14, v15, v16
	v_lshlrev_b32_e32 v14, 7, v20
	v_and_b32_e32 v15, 0x70, v26
	s_waitcnt vmcnt(0)
; #define SLOAD(i, k0) do { sr_[i].vs0 = *(const bf16x8*)(&Vh[(size_t)((k0) + sr) * LDX + sc]); sr_[i].vs1 = *(const bf16x8*)(&Vh[(size_t)((k0) + 32 + sr) * LDX + sc]); \
;     sr_[i].ks0 = *(const bf16x8*)(&Kh[(size_t)((k0) + kr) * LDX + kc]); } while (0)
; #define SWRITE(b, i) do { *(LAS bf16x8*)(V_lds + (b) * SHM_V + vst0) = sr_[i].vs0; *(LAS bf16x8*)(V_lds + (b) * SHM_V + vst1) = sr_[i].vs1; \
;     *(LAS bf16x8*)(K_lds + (b) * SHM_K + kst) = sr_[i].ks0; } while (0)
; __device__ __forceinline__ void attn_pass(const bf16_t* __restrict__ Qb, const bf16_t* __restrict__ Kh, const bf16_t* __restrict__ Vh, int seq, LAS char* lds, const int wid, f32x16 (&o)[4], float (&rli)[16]) {
;     ...
;     SLOAD(0, 0); asm volatile("s_waitcnt vmcnt(0)" ::: "memory"); SWRITE(0, 0);
;     SLOAD(1, KVBLK); SLOAD(0, 2 * KVBLK);
;     __syncthreads();
	v_bitop3_b32 v54, v22, v14, v15 bitop3:0xde
	v_add_u32_e32 v69, 0, v234
	v_add_u32_e32 v235, s60, v54
	v_lshlrev_b32_e32 v230, 4, v0
	v_lshlrev_b32_e32 v238, 7, v57
	v_add_u32_e32 v241, s60, v238
	s_waitcnt vmcnt(6)
	ds_write_b128 v68, v[2:5]
	v_add_co_u32_e32 v2, vcc, s34, v50
	s_mov_b32 s34, 0x18000
	s_nop 0
	v_addc_co_u32_e32 v3, vcc, 0, v51, vcc
	v_add_co_u32_e32 v4, vcc, s34, v50
	s_waitcnt vmcnt(5)
	ds_write_b128 v69, v[6:9]
	s_waitcnt vmcnt(4)
	ds_write_b128 v235, v[10:13]
	v_addc_co_u32_e32 v5, vcc, 0, v51, vcc
	s_mov_b32 s34, 0xcf10000
	global_load_dwordx4 v[34:37], v[2:3], off
	global_load_dwordx4 v[38:41], v[4:5], off
	v_add_co_u32_e32 v2, vcc, s34, v52
	s_mov_b32 s34, 0x20000
	s_nop 0
	v_addc_co_u32_e32 v3, vcc, 0, v53, vcc
	global_load_dwordx4 v[42:45], v[2:3], off offset:128
	v_add_co_u32_e32 v2, vcc, s34, v50
	s_mov_b32 s34, 0x28000
	s_nop 0
	v_addc_co_u32_e32 v3, vcc, 0, v51, vcc
	v_add_co_u32_e32 v4, vcc, s34, v50
	s_mov_b32 s34, 0xcf20000
	s_nop 0
	v_addc_co_u32_e32 v5, vcc, 0, v51, vcc
	global_load_dwordx4 v[160:163], v[2:3], off
	global_load_dwordx4 v[164:167], v[4:5], off
	v_add_co_u32_e32 v2, vcc, s34, v52
	s_movk_i32 s34, 0x70
	v_bitop3_b32 v240, v58, v230, s34 bitop3:0x6c
	v_addc_co_u32_e32 v3, vcc, 0, v53, vcc
	v_add_u32_e32 v0, v241, v240
	global_load_dwordx4 v[168:171], v[2:3], off offset:128
	s_waitcnt lgkmcnt(0)
	s_barrier
; #define SWRITE(b, i) do { *(LAS bf16x8*)(V_lds + (b) * SHM_V + vst0) = sr_[i].vs0; *(LAS bf16x8*)(V_lds + (b) * SHM_V + vst1) = sr_[i].vs1; \
;     *(LAS bf16x8*)(K_lds + (b) * SHM_K + kst) = sr_[i].ks0; } while (0)
; __device__ __forceinline__ void partialSM(f32x16& p0, f32x16& p1, float& mhat, f32x16& negm, float& alpha, const bool first) {
;     constexpr float THRL = THR * 1.4426950408889634f;
;     float pmax = p0[0];
; #pragma unroll
;     for (int r = 1; r < 16; ++r) pmax = fmaxf(pmax, p0[r]);
; #pragma unroll
;     for (int r = 0; r < 16; ++r) pmax = fmaxf(pmax, p1[r]);
;     { auto rr = __builtin_amdgcn_permlane32_swap(__float_as_uint(pmax), __float_as_uint(pmax), false, false);
;       pmax = fmaxf(__uint_as_float(rr[0]), __uint_as_float(rr[1])); }
;     if (__builtin_expect(!first && __all(pmax <= THRL), 1)) { alpha = 1.f; }
;     else { const float dl = first ? pmax : fmaxf(pmax, 0.f); mhat += dl; alpha = first ? 0.f : __builtin_amdgcn_exp2f(-dl);
; #pragma unroll
;         for (int r = 0; r < 16; ++r) { p0[r] -= dl; p1[r] -= dl; }
; #pragma unroll
;         for (int r = 0; r < 16; ++r) negm[r] = -mhat; }
; #pragma unroll
;     for (int r = 0; r < 16; ++r) p0[r] = __builtin_amdgcn_exp2f(p0[r]);
; }
; __device__ __forceinline__ void finishSM(f32x16& p0, f32x16& p1, float alpha, float& l_reg, bf16x8& pa0, bf16x8& pa1, bf16x8& pa2, bf16x8& pa3) {
; #pragma unroll
;     for (int r = 0; r < 16; ++r) p1[r] = __builtin_amdgcn_exp2f(p1[r]);
;     float ps = 0;
; #pragma unroll
;     for (int r = 0; r < 16; ++r) ps += p0[r];
; #pragma unroll
;     for (int r = 0; r < 16; ++r) ps += p1[r];
;     { auto rr = __builtin_amdgcn_permlane32_swap(__float_as_uint(ps), __float_as_uint(ps), false, false);
;       ps = __uint_as_float(rr[0]) + __uint_as_float(rr[1]); }
;     l_reg = l_reg * alpha + ps;
;     ...
;     PK4(p0, 0, pa0); PK4(p0, 8, pa1); PK4(p1, 0, pa2); PK4(p1, 8, pa3);
;     ...
; }
; __device__ __forceinline__ void attn_pass(const bf16_t* __restrict__ Qb, const bf16_t* __restrict__ Kh, const bf16_t* __restrict__ Vh, int seq, LAS char* lds, const int wid, f32x16 (&o)[4], float (&rli)[16]) {
;     ...
;     qkt(pA0, pA1, K_lds, qr, negm, r32, hi);
;     partialSM(pA0, pA1, mhat, negm, alA, true); finishSM(pA0, pA1, alA, l_reg, pa0, pa1, pa2, pa3);
;     SWAIT(); SWRITE(1, 1);
;     SLOAD(1, 3 * KVBLK);
;     SWAIT(); SWRITE(2, 0);
;     __syncthreads();
	ds_read_b128 v[2:5], v0
	ds_read_b128 v[18:21], v0 offset:4096
	s_waitcnt vmcnt(9) lgkmcnt(1)
	v_mfma_f32_32x32x16_bf16 v[2:17], v[2:5], v[156:159], 0
	v_add_u32_e32 v0, 32, v230
	v_bitop3_b32 v239, v0, v58, s34 bitop3:0x78
	v_add_u32_e32 v0, v241, v239
	ds_read_b128 v[60:63], v0
	ds_read_b128 v[64:67], v0 offset:4096
	v_add_u32_e32 v0, 64, v230
	v_bitop3_b32 v236, v0, v58, s34 bitop3:0x78
	v_add_u32_e32 v0, v241, v236
	s_waitcnt lgkmcnt(2)
	v_mfma_f32_32x32x16_bf16 v[18:33], v[18:21], v[156:159], 0
	s_waitcnt vmcnt(8) lgkmcnt(1)
	v_mfma_f32_32x32x16_bf16 v[2:17], v[60:63], v[152:155], v[2:17]
	s_waitcnt lgkmcnt(0)
	v_mfma_f32_32x32x16_bf16 v[18:33], v[64:67], v[152:155], v[18:33]
	ds_read_b128 v[60:63], v0
	ds_read_b128 v[64:67], v0 offset:4096
	v_add_u32_e32 v0, 0x60, v230
	v_bitop3_b32 v237, v0, v58, s34 bitop3:0x78
	v_add_u32_e32 v0, v241, v237
	s_mov_b32 s34, 0x30000
	s_waitcnt vmcnt(7) lgkmcnt(1)
	v_mfma_f32_32x32x16_bf16 v[2:17], v[60:63], v[148:151], v[2:17]
	s_waitcnt lgkmcnt(0)
	v_mfma_f32_32x32x16_bf16 v[18:33], v[64:67], v[148:151], v[18:33]
	ds_read_b128 v[60:63], v0
	ds_read_b128 v[64:67], v0 offset:4096
	s_waitcnt vmcnt(3)
	s_waitcnt vmcnt(6) lgkmcnt(1)
	v_mfma_f32_32x32x16_bf16 v[2:17], v[60:63], v[144:147], v[2:17]
	s_waitcnt lgkmcnt(0)
	v_mfma_f32_32x32x16_bf16 v[18:33], v[64:67], v[144:147], v[18:33]
	s_nop 9
	v_max_f32_e32 v0, v2, v3
	v_max3_f32 v0, v0, v4, v5
	v_max3_f32 v0, v0, v6, v7
	v_max3_f32 v0, v0, v8, v9
	v_max3_f32 v0, v0, v10, v11
	v_max3_f32 v0, v0, v12, v13
	v_max3_f32 v0, v0, v14, v15
	v_max3_f32 v0, v0, v16, v17
	v_max3_f32 v0, v0, v18, v19
	v_max3_f32 v0, v0, v20, v21
	v_max3_f32 v0, v0, v22, v23
	v_max3_f32 v0, v0, v24, v25
	v_max3_f32 v0, v0, v26, v27
	v_max3_f32 v0, v0, v28, v29
	v_max3_f32 v0, v0, v30, v31
	v_max3_f32 v0, v0, v32, v33
	v_mov_b32_e32 v55, v0
	s_nop 1
	v_permlane32_swap_b32_e32 v0, v55
	v_max_f32_e32 v55, v0, v55
	v_sub_f32_e32 v0, v2, v55
	v_sub_f32_e32 v2, v18, v55
	v_sub_f32_e32 v3, v3, v55
	v_exp_f32_e32 v63, v2
	v_add_co_u32_e32 v2, vcc, s34, v50
	v_sub_f32_e32 v4, v4, v55
	v_exp_f32_e32 v60, v3
	v_addc_co_u32_e32 v3, vcc, 0, v51, vcc
	s_mov_b32 s34, 0x38000
	v_sub_f32_e32 v5, v5, v55
	v_exp_f32_e32 v61, v4
	v_add_co_u32_e32 v4, vcc, s34, v50
	v_exp_f32_e32 v62, v5
	s_nop 0
	v_addc_co_u32_e32 v5, vcc, 0, v51, vcc
	global_load_dwordx4 v[172:175], v[2:3], off
	global_load_dwordx4 v[176:179], v[4:5], off
	v_add_co_u32_e32 v2, vcc, 0xcf30000, v52
	v_sub_f32_e32 v18, v19, v55
	s_nop 0
	v_addc_co_u32_e32 v3, vcc, 0, v53, vcc
	global_load_dwordx4 v[180:183], v[2:3], off offset:128
	v_sub_f32_e32 v19, v20, v55
	v_sub_f32_e32 v20, v21, v55
	v_sub_f32_e32 v21, v22, v55
	v_sub_f32_e32 v22, v23, v55
	v_sub_f32_e32 v23, v24, v55
	v_sub_f32_e32 v24, v25, v55
	v_sub_f32_e32 v25, v26, v55
	v_sub_f32_e32 v26, v27, v55
	v_sub_f32_e32 v27, v28, v55
	v_sub_f32_e32 v28, v29, v55
	v_sub_f32_e32 v29, v30, v55
	v_sub_f32_e32 v30, v31, v55
	v_sub_f32_e32 v31, v32, v55
	v_sub_f32_e32 v32, v33, v55
	v_exp_f32_e32 v33, v0
	v_sub_f32_e32 v6, v6, v55
	v_sub_f32_e32 v7, v7, v55
	v_exp_f32_e32 v6, v6
	v_add_f32_e32 v0, 0, v33
	v_sub_f32_e32 v8, v8, v55
	v_exp_f32_e32 v7, v7
	v_add_f32_e32 v0, v60, v0
	v_sub_f32_e32 v9, v9, v55
	v_exp_f32_e32 v8, v8
	v_add_f32_e32 v0, v61, v0
	v_sub_f32_e32 v10, v10, v55
	v_exp_f32_e32 v9, v9
	v_add_f32_e32 v0, v62, v0
	v_sub_f32_e32 v11, v11, v55
	v_exp_f32_e32 v10, v10
	v_add_f32_e32 v0, v6, v0
	v_sub_f32_e32 v12, v12, v55
	v_exp_f32_e32 v11, v11
	v_add_f32_e32 v0, v7, v0
	v_sub_f32_e32 v13, v13, v55
	v_exp_f32_e32 v12, v12
	v_add_f32_e32 v0, v8, v0
	v_sub_f32_e32 v14, v14, v55
	v_exp_f32_e32 v13, v13
	v_add_f32_e32 v0, v9, v0
	v_sub_f32_e32 v15, v15, v55
	v_exp_f32_e32 v14, v14
	v_add_f32_e32 v0, v10, v0
	v_sub_f32_e32 v16, v16, v55
	v_exp_f32_e32 v15, v15
	v_add_f32_e32 v0, v11, v0
	v_sub_f32_e32 v17, v17, v55
	v_exp_f32_e32 v16, v16
	v_add_f32_e32 v0, v12, v0
	v_exp_f32_e32 v17, v17
	v_add_f32_e32 v0, v13, v0
	v_add_f32_e32 v0, v14, v0
	v_exp_f32_e32 v18, v18
	v_add_f32_e32 v0, v15, v0
	v_exp_f32_e32 v19, v19
	v_add_f32_e32 v0, v16, v0
	v_exp_f32_e32 v20, v20
	v_add_f32_e32 v0, v17, v0
	v_exp_f32_e32 v21, v21
	v_add_f32_e32 v0, v63, v0
	v_exp_f32_e32 v22, v22
	v_add_f32_e32 v0, v18, v0
	v_exp_f32_e32 v23, v23
	v_add_f32_e32 v0, v19, v0
	v_exp_f32_e32 v24, v24
	v_add_f32_e32 v0, v20, v0
	v_exp_f32_e32 v25, v25
	v_add_f32_e32 v0, v21, v0
	v_exp_f32_e32 v26, v26
	v_add_f32_e32 v0, v22, v0
	v_exp_f32_e32 v27, v27
	v_add_f32_e32 v0, v23, v0
	v_exp_f32_e32 v28, v28
	v_add_f32_e32 v0, v24, v0
	v_exp_f32_e32 v29, v29
	v_add_f32_e32 v0, v25, v0
	v_exp_f32_e32 v30, v30
	v_add_f32_e32 v0, v26, v0
	v_exp_f32_e32 v31, v31
	v_add_f32_e32 v0, v27, v0
	v_exp_f32_e32 v32, v32
	v_add_f32_e32 v0, v28, v0
	v_add_f32_e32 v0, v29, v0
	v_add_u32_e32 v3, 0, v54
	v_add_f32_e32 v0, v30, v0
	v_add_u32_e32 v4, 0x12000, v3
	v_add_f32_e32 v0, v31, v0
	s_waitcnt vmcnt(8)
	ds_write_b128 v68, v[34:37] offset:16384
	s_waitcnt vmcnt(7)
	ds_write_b128 v69, v[38:41] offset:16384
	s_waitcnt vmcnt(6)
	ds_write_b128 v4, v[42:45]
	v_add_f32_e32 v0, v32, v0
	s_waitcnt vmcnt(3)
	v_mov_b32_e32 v2, v0
	v_cvt_pk_bf16_f32 v184, v33, v60
	v_cvt_pk_bf16_f32 v185, v61, v62
	v_cvt_pk_bf16_f32 v186, v6, v7
	v_cvt_pk_bf16_f32 v187, v8, v9
	v_cvt_pk_bf16_f32 v188, v10, v11
	v_cvt_pk_bf16_f32 v189, v12, v13
	v_cvt_pk_bf16_f32 v190, v14, v15
	v_cvt_pk_bf16_f32 v191, v16, v17
	v_cvt_pk_bf16_f32 v192, v63, v18
	v_cvt_pk_bf16_f32 v193, v19, v20
	v_cvt_pk_bf16_f32 v194, v21, v22
	v_cvt_pk_bf16_f32 v195, v23, v24
	v_cvt_pk_bf16_f32 v196, v25, v26
	v_cvt_pk_bf16_f32 v197, v27, v28
	v_cvt_pk_bf16_f32 v198, v29, v30
	v_cvt_pk_bf16_f32 v199, v31, v32
	v_permlane32_swap_b32_e32 v0, v2
	v_permlane32_swap_b32_e32 v184, v186
	v_permlane32_swap_b32_e32 v185, v187
	v_permlane32_swap_b32_e32 v188, v190
	v_permlane32_swap_b32_e32 v189, v191
	v_permlane32_swap_b32_e32 v192, v194
	v_permlane32_swap_b32_e32 v193, v195
	v_permlane32_swap_b32_e32 v196, v198
	v_permlane32_swap_b32_e32 v197, v199
	v_add_u32_e32 v3, 0x14000, v3
	s_and_b64 vcc, exec, s[46:47]
	s_waitcnt vmcnt(5)
	ds_write_b128 v68, v[160:163] offset:32768
	s_waitcnt vmcnt(4)
	ds_write_b128 v69, v[164:167] offset:32768
	s_waitcnt vmcnt(3)
	ds_write_b128 v3, v[168:171]
	s_waitcnt lgkmcnt(0)
	s_barrier
	s_cbranch_vccnz .LBB0_619
	s_waitcnt lgkmcnt(0)
	s_barrier

; __device__ __forceinline__ void partialSM(f32x16& p0, f32x16& p1, float& mhat, f32x16& negm, float& alpha, const bool first) {
;     ...
;     for (int r = 0; r < 16; ++r) p0[r] = __builtin_amdgcn_exp2f(p0[r]);
; }
; __device__ __forceinline__ void finishSM(f32x16& p0, f32x16& p1, float alpha, float& l_reg, bf16x8& pa0, bf16x8& pa1, bf16x8& pa2, bf16x8& pa3) {
; #pragma unroll
;     for (int r = 0; r < 16; ++r) p1[r] = __builtin_amdgcn_exp2f(p1[r]);
;     float ps = 0;
; #pragma unroll
;     for (int r = 0; r < 16; ++r) ps += p0[r];
; #pragma unroll
;     for (int r = 0; r < 16; ++r) ps += p1[r];
;     { auto rr = __builtin_amdgcn_permlane32_swap(__float_as_uint(ps), __float_as_uint(ps), false, false);
;       ps = __uint_as_float(rr[0]) + __uint_as_float(rr[1]); }
;     l_reg = l_reg * alpha + ps;
.LBB0_629:
	v_exp_f32_e32 v2, v128
	v_exp_f32_e32 v3, v129
	v_exp_f32_e32 v4, v130
	v_exp_f32_e32 v5, v131
	v_exp_f32_e32 v6, v132
	v_add_f32_e32 v132, 0, v2
	v_exp_f32_e32 v7, v133
	v_add_f32_e32 v132, v3, v132
	v_exp_f32_e32 v8, v134
	v_add_f32_e32 v132, v4, v132
	v_exp_f32_e32 v9, v135
	v_add_f32_e32 v132, v5, v132
	v_exp_f32_e32 v10, v136
	v_add_f32_e32 v132, v6, v132
	v_exp_f32_e32 v11, v137
	v_add_f32_e32 v132, v7, v132
	v_exp_f32_e32 v12, v138
	v_add_f32_e32 v132, v8, v132
	v_exp_f32_e32 v13, v139
	v_add_f32_e32 v132, v9, v132
	v_exp_f32_e32 v128, v140
	v_add_f32_e32 v132, v10, v132
	v_exp_f32_e32 v129, v141
	v_add_f32_e32 v132, v11, v132
	v_exp_f32_e32 v130, v142
	v_add_f32_e32 v132, v12, v132
	v_exp_f32_e32 v131, v143
	v_add_f32_e32 v132, v13, v132
	v_exp_f32_e32 v112, v112
	v_add_f32_e32 v132, v128, v132
	v_exp_f32_e32 v113, v113
	v_add_f32_e32 v132, v129, v132
	v_exp_f32_e32 v114, v114
	v_add_f32_e32 v132, v130, v132
	v_exp_f32_e32 v115, v115
	v_add_f32_e32 v132, v131, v132
	v_exp_f32_e32 v116, v116
	v_add_f32_e32 v132, v112, v132
	v_exp_f32_e32 v117, v117
	v_add_f32_e32 v132, v113, v132
	v_exp_f32_e32 v118, v118
	v_add_f32_e32 v132, v114, v132
	v_exp_f32_e32 v119, v119
	v_add_f32_e32 v132, v115, v132
	v_exp_f32_e32 v120, v120
	v_add_f32_e32 v132, v116, v132
	v_exp_f32_e32 v121, v121
	v_add_f32_e32 v132, v117, v132
	v_exp_f32_e32 v122, v122
	v_add_f32_e32 v132, v118, v132
	v_exp_f32_e32 v123, v123
	v_add_f32_e32 v132, v119, v132
	v_exp_f32_e32 v124, v124
	v_add_f32_e32 v132, v120, v132
	v_exp_f32_e32 v125, v125
	v_add_f32_e32 v132, v121, v132
	v_exp_f32_e32 v126, v126
	v_add_f32_e32 v132, v122, v132
	v_exp_f32_e32 v127, v127
	v_add_f32_e32 v132, v123, v132
	v_add_f32_e32 v132, v124, v132
	v_add_f32_e32 v132, v125, v132
	v_add_f32_e32 v132, v126, v132
	v_add_f32_e32 v190, v127, v132
	s_waitcnt lgkmcnt(0)
	s_barrier
; #define LAS __attribute__((address_space(3)))
; __device__ __forceinline__ void finishSM(f32x16& p0, f32x16& p1, float alpha, float& l_reg, bf16x8& pa0, bf16x8& pa1, bf16x8& pa2, bf16x8& pa3) {
; #pragma unroll
;     for (int r = 0; r < 16; ++r) p1[r] = __builtin_amdgcn_exp2f(p1[r]);
;     float ps = 0;
; #pragma unroll
;     for (int r = 0; r < 16; ++r) ps += p0[r];
; #pragma unroll
;     for (int r = 0; r < 16; ++r) ps += p1[r];
;     { auto rr = __builtin_amdgcn_permlane32_swap(__float_as_uint(ps), __float_as_uint(ps), false, false);
;       ps = __uint_as_float(rr[0]) + __uint_as_float(rr[1]); }
;     l_reg = l_reg * alpha + ps;
;     ...
;     PK4(p0, 0, pa0); PK4(p0, 8, pa1); PK4(p1, 0, pa2); PK4(p1, 8, pa3);
;     ...
; }
; __device__ __forceinline__ void qkt(f32x16& p0, f32x16& p1, const LAS char* Ks, const bf16x8* qr, const f32x16& negm, int r32, int hi) {
; #pragma unroll
;     for (int d0 = 0; d0 < 4; ++d0) { const int cb = (d0 * 16 + hi * 8) * 2;
;         const bf16x8 b0 = *(const LAS bf16x8*)(Ks + KSWZ(r32, cb));
;         const bf16x8 b1 = *(const LAS bf16x8*)(Ks + KSWZ(32 + r32, cb));
;         if (d0 == 0) { p0 = __builtin_amdgcn_mfma_f32_32x32x16_bf16(b0, qr[0], negm, 0, 0, 0); p1 = __builtin_amdgcn_mfma_f32_32x32x16_bf16(b1, qr[0], negm, 0, 0, 0); }
;         else { p0 = __builtin_amdgcn_mfma_f32_32x32x16_bf16(b0, qr[d0], p0, 0, 0, 0); p1 = __builtin_amdgcn_mfma_f32_32x32x16_bf16(b1, qr[d0], p1, 0, 0, 0); } }
; }
; __device__ __forceinline__ int v_st(int k, int c) { const int kk = (k & ~0xC) | ((k & 4) << 1) | ((k & 8) >> 1); return ((kk >> 3) * 4 + (c >> 5)) * 512 + ((kk & 7) * 32 + (c & 31)) * 2; }
; __device__ __forceinline__ int v_rd_base(int lane) { return ((lane & 3) << 3) | (((lane >> 2) & 3) << 6) | (((lane >> 4) & 1) << 5) | (((lane >> 5) & 1) << 8); }
; template <int OFF> __device__ __forceinline__ s16x4 tr_read(int vb) {
;     s16x4 r; asm volatile("ds_read_b64_tr_b16 %0, %1 offset:%2" : "=&v"(r) : "v"(vb), "i"(OFF) : "memory"); return r;
; }
; template <int D0> __device__ __forceinline__ void pv_one(f32x16& od, int vb, bf16x8 pa0, bf16x8 pa1, bf16x8 pa2, bf16x8 pa3) {
;     const s16x4 l0 = tr_read<v_rd_off(D0, 0, 0)>(vb), h0 = tr_read<v_rd_off(D0, 0, 1)>(vb), l1 = tr_read<v_rd_off(D0, 1, 0)>(vb), h1 = tr_read<v_rd_off(D0, 1, 1)>(vb);
	v_mov_b32_e32 v191, v190
	s_nop 1
	v_permlane32_swap_b32_e32 v190, v191
	v_cvt_pk_bf16_f32 v2, v2, v3
	v_cvt_pk_bf16_f32 v3, v4, v5
	v_cvt_pk_bf16_f32 v4, v6, v7
	v_cvt_pk_bf16_f32 v5, v8, v9
	v_cvt_pk_bf16_f32 v6, v10, v11
	v_cvt_pk_bf16_f32 v7, v12, v13
	v_cvt_pk_bf16_f32 v8, v128, v129
	v_cvt_pk_bf16_f32 v9, v130, v131
	v_cvt_pk_bf16_f32 v10, v112, v113
	v_cvt_pk_bf16_f32 v11, v114, v115
	v_cvt_pk_bf16_f32 v12, v116, v117
	v_cvt_pk_bf16_f32 v13, v118, v119
	v_cvt_pk_bf16_f32 v184, v120, v121
	v_cvt_pk_bf16_f32 v185, v122, v123
	v_cvt_pk_bf16_f32 v186, v124, v125
	v_cvt_pk_bf16_f32 v187, v126, v127
	v_permlane32_swap_b32_e32 v2, v4
	v_permlane32_swap_b32_e32 v3, v5
	v_permlane32_swap_b32_e32 v6, v8
	v_permlane32_swap_b32_e32 v7, v9
	v_permlane32_swap_b32_e32 v10, v12
	v_permlane32_swap_b32_e32 v11, v13
	v_permlane32_swap_b32_e32 v184, v186
	v_permlane32_swap_b32_e32 v185, v187
	s_setprio 1
	s_and_b32 s4, s18, 0x6000
	v_add_u32_e32 v200, s4, v241
	v_add_u32_e32 v112, v200, v240
	ds_read_b128 v[192:195], v112 offset:4096
	ds_read_b128 v[112:115], v112
	v_add_u32_e32 v196, v200, v239
	s_waitcnt lgkmcnt(0)
	v_mfma_f32_32x32x16_bf16 v[128:143], v[112:115], v[156:159], v[96:111]
	v_mfma_f32_32x32x16_bf16 v[112:127], v[192:195], v[156:159], v[96:111]
	ds_read_b128 v[192:195], v196 offset:4096
	ds_read_b128 v[196:199], v196
	s_waitcnt lgkmcnt(1)
	v_mfma_f32_32x32x16_bf16 v[112:127], v[192:195], v[152:155], v[112:127]
	s_waitcnt lgkmcnt(0)
	v_mfma_f32_32x32x16_bf16 v[128:143], v[196:199], v[152:155], v[128:143]
	v_add_u32_e32 v196, v200, v236
	ds_read_b128 v[192:195], v196 offset:4096
	ds_read_b128 v[196:199], v196
	s_waitcnt lgkmcnt(1)
	v_mfma_f32_32x32x16_bf16 v[112:127], v[192:195], v[148:151], v[112:127]
	s_waitcnt lgkmcnt(0)
	v_mfma_f32_32x32x16_bf16 v[128:143], v[196:199], v[148:151], v[128:143]
	v_add_u32_e32 v196, v200, v237
	ds_read_b128 v[192:195], v196 offset:4096
	ds_read_b128 v[196:199], v196
	v_lshl_add_u32 v200, s38, 14, v242
	ds_read_b64_tr_b16 v[172:173], v200 offset:0
	ds_read_b64_tr_b16 v[174:175], v200 offset:0x800
	ds_read_b64_tr_b16 v[176:177], v200 offset:0x1000
	ds_read_b64_tr_b16 v[178:179], v200 offset:0x1800
	s_waitcnt lgkmcnt(5)
	v_mfma_f32_32x32x16_bf16 v[112:127], v[192:195], v[144:147], v[112:127]
	ds_read_b64_tr_b16 v[220:221], v200 offset:0x2000
	ds_read_b64_tr_b16 v[222:223], v200 offset:0x2800
	s_waitcnt lgkmcnt(6)
	v_mfma_f32_32x32x16_bf16 v[128:143], v[196:199], v[144:147], v[128:143]
	ds_read_b64_tr_b16 v[244:245], v200 offset:0x3000
	ds_read_b64_tr_b16 v[246:247], v200 offset:0x3800
	s_waitcnt lgkmcnt(6)
	v_mfma_f32_32x32x16_bf16 v[64:79], v[2:5], v[172:175], v[64:79]
	ds_read_b64_tr_b16 v[192:193], v200 offset:0x200
	ds_read_b64_tr_b16 v[194:195], v200 offset:0xa00
	s_waitcnt lgkmcnt(6)
	v_mfma_f32_32x32x16_bf16 v[64:79], v[6:9], v[176:179], v[64:79]
	ds_read_b64_tr_b16 v[196:197], v200 offset:0x1200
	ds_read_b64_tr_b16 v[198:199], v200 offset:0x1a00
	s_waitcnt lgkmcnt(6)
	v_mfma_f32_32x32x16_bf16 v[64:79], v[10:13], v[220:223], v[64:79]
	ds_read_b64_tr_b16 v[220:221], v200 offset:0x2200
	ds_read_b64_tr_b16 v[222:223], v200 offset:0x2a00
	s_waitcnt lgkmcnt(6)
	v_mfma_f32_32x32x16_bf16 v[64:79], v[184:187], v[244:247], v[64:79]
	ds_read_b64_tr_b16 v[244:245], v200 offset:0x3200
	ds_read_b64_tr_b16 v[246:247], v200 offset:0x3a00
	s_waitcnt lgkmcnt(6)
	v_mfma_f32_32x32x16_bf16 v[48:63], v[2:5], v[192:195], v[48:63]
	ds_read_b64_tr_b16 v[192:193], v200 offset:0x400
	ds_read_b64_tr_b16 v[194:195], v200 offset:0xc00
	s_waitcnt lgkmcnt(6)
	v_mfma_f32_32x32x16_bf16 v[48:63], v[6:9], v[196:199], v[48:63]
	ds_read_b64_tr_b16 v[196:197], v200 offset:0x1400
	ds_read_b64_tr_b16 v[198:199], v200 offset:0x1c00
	s_waitcnt lgkmcnt(6)
	v_mfma_f32_32x32x16_bf16 v[48:63], v[10:13], v[220:223], v[48:63]
	ds_read_b64_tr_b16 v[220:221], v200 offset:0x2400
	ds_read_b64_tr_b16 v[222:223], v200 offset:0x2c00
	s_waitcnt lgkmcnt(6)
	v_mfma_f32_32x32x16_bf16 v[48:63], v[184:187], v[244:247], v[48:63]
	ds_read_b64_tr_b16 v[244:245], v200 offset:0x3400
	ds_read_b64_tr_b16 v[246:247], v200 offset:0x3c00
	s_waitcnt lgkmcnt(6)
	v_mfma_f32_32x32x16_bf16 v[32:47], v[2:5], v[192:195], v[32:47]
	ds_read_b64_tr_b16 v[192:193], v200 offset:0x600
	ds_read_b64_tr_b16 v[194:195], v200 offset:0xe00
	s_waitcnt lgkmcnt(6)
	v_mfma_f32_32x32x16_bf16 v[32:47], v[6:9], v[196:199], v[32:47]
	ds_read_b64_tr_b16 v[196:197], v200 offset:0x1600
	ds_read_b64_tr_b16 v[198:199], v200 offset:0x1e00
	s_waitcnt lgkmcnt(6)
	v_mfma_f32_32x32x16_bf16 v[32:47], v[10:13], v[220:223], v[32:47]
	ds_read_b64_tr_b16 v[220:221], v200 offset:0x2600
	ds_read_b64_tr_b16 v[222:223], v200 offset:0x2e00
	s_waitcnt lgkmcnt(6)
	v_mfma_f32_32x32x16_bf16 v[32:47], v[184:187], v[244:247], v[32:47]
	ds_read_b64_tr_b16 v[244:245], v200 offset:0x3600
	ds_read_b64_tr_b16 v[246:247], v200 offset:0x3e00
	s_waitcnt lgkmcnt(6)
	v_mfma_f32_32x32x16_bf16 v[16:31], v[2:5], v[192:195], v[16:31]
	s_waitcnt lgkmcnt(4)
	v_mfma_f32_32x32x16_bf16 v[16:31], v[6:9], v[196:199], v[16:31]
	s_waitcnt lgkmcnt(2)
	v_mfma_f32_32x32x16_bf16 v[16:31], v[10:13], v[220:223], v[16:31]
	s_waitcnt lgkmcnt(0)
	v_mfma_f32_32x32x16_bf16 v[16:31], v[184:187], v[244:247], v[16:31]
	s_setprio 0
	s_waitcnt lgkmcnt(0)
	s_barrier
	s_andn2_b64 vcc, exec, s[2:3]
	s_cbranch_vccnz .LBB0_631
	s_and_b32 s2, s35, 3
	s_lshl_b32 s3, s2, 14
	s_add_i32 s3, s3, 0
	v_add_u32_e32 v2, s3, v233
	v_add_u32_e32 v3, s3, v234
	v_lshl_add_u32 v4, s2, 13, v235
	s_waitcnt vmcnt(2)
	ds_write_b128 v2, v[160:163]
	s_waitcnt vmcnt(1)
	ds_write_b128 v3, v[164:167]
	s_waitcnt vmcnt(0)
	ds_write_b128 v4, v[168:171]

; #define LAS __attribute__((address_space(3)))
; #define SBAR() __builtin_amdgcn_sched_barrier(0)
; __device__ __forceinline__ void qkt(f32x16& p0, f32x16& p1, const LAS char* Ks, const bf16x8* qr, const f32x16& negm, int r32, int hi) {
; #pragma unroll
;     for (int d0 = 0; d0 < 4; ++d0) { const int cb = (d0 * 16 + hi * 8) * 2;
;         const bf16x8 b0 = *(const LAS bf16x8*)(Ks + KSWZ(r32, cb));
;         const bf16x8 b1 = *(const LAS bf16x8*)(Ks + KSWZ(32 + r32, cb));
;         if (d0 == 0) { p0 = __builtin_amdgcn_mfma_f32_32x32x16_bf16(b0, qr[0], negm, 0, 0, 0); p1 = __builtin_amdgcn_mfma_f32_32x32x16_bf16(b1, qr[0], negm, 0, 0, 0); }
;         else { p0 = __builtin_amdgcn_mfma_f32_32x32x16_bf16(b0, qr[d0], p0, 0, 0, 0); p1 = __builtin_amdgcn_mfma_f32_32x32x16_bf16(b1, qr[d0], p1, 0, 0, 0); } }
; }
; __device__ __forceinline__ int v_st(int k, int c) { const int kk = (k & ~0xC) | ((k & 4) << 1) | ((k & 8) >> 1); return ((kk >> 3) * 4 + (c >> 5)) * 512 + ((kk & 7) * 32 + (c & 31)) * 2; }
; __device__ __forceinline__ int v_rd_base(int lane) { return ((lane & 3) << 3) | (((lane >> 2) & 3) << 6) | (((lane >> 4) & 1) << 5) | (((lane >> 5) & 1) << 8); }
; template <int OFF> __device__ __forceinline__ s16x4 tr_read(int vb) {
;     s16x4 r; asm volatile("ds_read_b64_tr_b16 %0, %1 offset:%2" : "=&v"(r) : "v"(vb), "i"(OFF) : "memory"); return r;
; }
; template <int D0> __device__ __forceinline__ void pv_one(f32x16& od, int vb, bf16x8 pa0, bf16x8 pa1, bf16x8 pa2, bf16x8 pa3) {
;     const s16x4 l0 = tr_read<v_rd_off(D0, 0, 0)>(vb), h0 = tr_read<v_rd_off(D0, 0, 1)>(vb), l1 = tr_read<v_rd_off(D0, 1, 0)>(vb), h1 = tr_read<v_rd_off(D0, 1, 1)>(vb);
;     const s16x4 l2 = tr_read<v_rd_off(D0, 2, 0)>(vb), h2 = tr_read<v_rd_off(D0, 2, 1)>(vb), l3 = tr_read<v_rd_off(D0, 3, 0)>(vb), h3 = tr_read<v_rd_off(D0, 3, 1)>(vb);
;     asm volatile("s_waitcnt lgkmcnt(0)" ::: "memory"); SBAR();
;     ...
;     od = __builtin_amdgcn_mfma_f32_32x32x16_bf16(pa0, PK(l0, h0), od, 0, 0, 0);
;     od = __builtin_amdgcn_mfma_f32_32x32x16_bf16(pa1, PK(l1, h1), od, 0, 0, 0);
;     od = __builtin_amdgcn_mfma_f32_32x32x16_bf16(pa2, PK(l2, h2), od, 0, 0, 0);
;     od = __builtin_amdgcn_mfma_f32_32x32x16_bf16(pa3, PK(l3, h3), od, 0, 0, 0);
;     ...
; }
; __device__ __forceinline__ void pv_d0(f32x16* o, int vb, bf16x8 pa0, bf16x8 pa1, bf16x8 pa2, bf16x8 pa3) {
.LBB0_639:
	v_mov_b64_e32 v[80:81], v[96:97]
	v_mov_b64_e32 v[82:83], v[98:99]
	v_mov_b64_e32 v[84:85], v[100:101]
	v_mov_b64_e32 v[86:87], v[102:103]
	v_mov_b64_e32 v[88:89], v[104:105]
	v_mov_b64_e32 v[90:91], v[106:107]
	v_mov_b64_e32 v[92:93], v[108:109]
	v_mov_b64_e32 v[94:95], v[110:111]
	s_setprio 1
	v_add_u32_e32 v0, s61, v238
	v_add_u32_e32 v6, v0, v240
	ds_read_b128 v[2:5], v6
	s_waitcnt lgkmcnt(0)
	v_mfma_f32_32x32x16_bf16 v[96:111], v[2:5], v[156:159], v[80:95]
	ds_read_b128 v[2:5], v6 offset:4096
	v_add_u32_e32 v6, v0, v239
	s_waitcnt lgkmcnt(0)
	v_mfma_f32_32x32x16_bf16 v[80:95], v[2:5], v[156:159], v[80:95]
	ds_read_b128 v[2:5], v6
	s_waitcnt lgkmcnt(0)
	v_mfma_f32_32x32x16_bf16 v[96:111], v[2:5], v[152:155], v[96:111]
	ds_read_b128 v[2:5], v6 offset:4096
	v_add_u32_e32 v6, v0, v236
	v_add_u32_e32 v0, v0, v237
	s_waitcnt lgkmcnt(0)
	v_mfma_f32_32x32x16_bf16 v[80:95], v[2:5], v[152:155], v[80:95]
	ds_read_b128 v[2:5], v6
	s_waitcnt lgkmcnt(0)
	v_mfma_f32_32x32x16_bf16 v[96:111], v[2:5], v[148:151], v[96:111]
	ds_read_b128 v[2:5], v6 offset:4096
	s_waitcnt lgkmcnt(0)
	v_mfma_f32_32x32x16_bf16 v[80:95], v[2:5], v[148:151], v[80:95]
	ds_read_b128 v[2:5], v0
	ds_read_b128 v[6:9], v0 offset:4096
	v_add_u32_e32 v0, s62, v232
	ds_read_b64_tr_b16 v[10:11], v0 offset:0
	ds_read_b64_tr_b16 v[12:13], v0 offset:0x800
	s_waitcnt lgkmcnt(1)
	v_mfma_f32_32x32x16_bf16 v[96:111], v[2:5], v[144:147], v[96:111]
	ds_read_b64_tr_b16 v[2:3], v0 offset:0x1000
	ds_read_b64_tr_b16 v[4:5], v0 offset:0x1800
	ds_read_b64_tr_b16 v[112:113], v0 offset:0x2000
	ds_read_b64_tr_b16 v[114:115], v0 offset:0x2800
	ds_read_b64_tr_b16 v[116:117], v0 offset:0x3000
	ds_read_b64_tr_b16 v[118:119], v0 offset:0x3800
	s_waitcnt lgkmcnt(0)
	s_waitcnt lgkmcnt(0)
	v_mfma_f32_32x32x16_bf16 v[80:95], v[6:9], v[144:147], v[80:95]
	v_mfma_f32_32x32x16_bf16 v[64:79], v[184:187], v[10:13], v[64:79]
	v_mfma_f32_32x32x16_bf16 v[64:79], v[188:191], v[2:5], v[64:79]
	ds_read_b64_tr_b16 v[2:3], v0 offset:0x200
	ds_read_b64_tr_b16 v[4:5], v0 offset:0xa00
	ds_read_b64_tr_b16 v[6:7], v0 offset:0x1200
	ds_read_b64_tr_b16 v[8:9], v0 offset:0x1a00
	ds_read_b64_tr_b16 v[10:11], v0 offset:0x2200
	ds_read_b64_tr_b16 v[12:13], v0 offset:0x2a00
	v_mfma_f32_32x32x16_bf16 v[64:79], v[192:195], v[112:115], v[64:79]
	ds_read_b64_tr_b16 v[112:113], v0 offset:0x3200
	ds_read_b64_tr_b16 v[114:115], v0 offset:0x3a00
	s_waitcnt lgkmcnt(0)
	v_mfma_f32_32x32x16_bf16 v[64:79], v[196:199], v[116:119], v[64:79]
	v_mfma_f32_32x32x16_bf16 v[48:63], v[184:187], v[2:5], v[48:63]
	ds_read_b64_tr_b16 v[2:3], v0 offset:0x400
	ds_read_b64_tr_b16 v[4:5], v0 offset:0xc00
	v_mfma_f32_32x32x16_bf16 v[48:63], v[188:191], v[6:9], v[48:63]
	ds_read_b64_tr_b16 v[6:7], v0 offset:0x1400
	ds_read_b64_tr_b16 v[8:9], v0 offset:0x1c00
	v_mfma_f32_32x32x16_bf16 v[48:63], v[192:195], v[10:13], v[48:63]
	ds_read_b64_tr_b16 v[10:11], v0 offset:0x2400
	ds_read_b64_tr_b16 v[12:13], v0 offset:0x2c00
	v_mfma_f32_32x32x16_bf16 v[48:63], v[196:199], v[112:115], v[48:63]
	ds_read_b64_tr_b16 v[112:113], v0 offset:0x3400
	ds_read_b64_tr_b16 v[114:115], v0 offset:0x3c00
	s_waitcnt lgkmcnt(0)
	v_mfma_f32_32x32x16_bf16 v[32:47], v[184:187], v[2:5], v[32:47]
	ds_read_b64_tr_b16 v[2:3], v0 offset:0x600
	ds_read_b64_tr_b16 v[4:5], v0 offset:0xe00
	v_mfma_f32_32x32x16_bf16 v[32:47], v[188:191], v[6:9], v[32:47]
	ds_read_b64_tr_b16 v[6:7], v0 offset:0x1600
	ds_read_b64_tr_b16 v[8:9], v0 offset:0x1e00
	v_mfma_f32_32x32x16_bf16 v[32:47], v[192:195], v[10:13], v[32:47]
	ds_read_b64_tr_b16 v[10:11], v0 offset:0x2600
	ds_read_b64_tr_b16 v[12:13], v0 offset:0x2e00
	v_mfma_f32_32x32x16_bf16 v[32:47], v[196:199], v[112:115], v[32:47]
	ds_read_b64_tr_b16 v[112:113], v0 offset:0x3600
	ds_read_b64_tr_b16 v[114:115], v0 offset:0x3e00
	s_waitcnt lgkmcnt(0)
	v_mfma_f32_32x32x16_bf16 v[16:31], v[184:187], v[2:5], v[16:31]
	v_mfma_f32_32x32x16_bf16 v[16:31], v[188:191], v[6:9], v[16:31]
	v_mfma_f32_32x32x16_bf16 v[16:31], v[192:195], v[10:13], v[16:31]
	v_mfma_f32_32x32x16_bf16 v[16:31], v[196:199], v[112:115], v[16:31]
	s_setprio 0
	v_max_f32_e32 v0, v96, v97
	v_max3_f32 v0, v0, v98, v99
	v_max3_f32 v0, v0, v100, v101
	v_max3_f32 v0, v0, v102, v103
	v_max3_f32 v0, v0, v104, v105
	v_max3_f32 v0, v0, v106, v107
	v_max3_f32 v0, v0, v108, v109
	v_max3_f32 v0, v0, v110, v111
	v_max3_f32 v0, v0, v80, v81
	v_max3_f32 v0, v0, v82, v83
	v_max3_f32 v0, v0, v84, v85
	v_max3_f32 v0, v0, v86, v87
	v_max3_f32 v0, v0, v88, v89
	v_max3_f32 v0, v0, v90, v91
	v_max3_f32 v0, v0, v92, v93
	v_max3_f32 v0, v0, v94, v95
	v_mov_b32_e32 v2, v0
	s_nop 1
	v_permlane32_swap_b32_e32 v0, v2
	v_max_f32_e32 v2, v2, v2
	v_max_f32_e32 v0, v0, v0
	s_waitcnt lgkmcnt(0)
	s_barrier
	v_max_f32_e32 v2, v0, v2
	v_cmp_ge_f32_e32 vcc, s24, v2
	s_cmp_eq_u64 vcc, exec
	v_mov_b32_e32 v0, 1.0
	s_cbranch_scc0 .LBB0_649
